# log2(e) folded into the q scale of the rope epilogue; exp2 applied directly to q.k in differential attention (128 multiplies per tile removed)
# speedup vs baseline: 1.0060x; 1.0028x over previous
.LBB0_222:
	v_lshlrev_b32_e32 v149, 7, v147
	v_and_b32_e32 v178, 0x3e780, v149
	v_lshl_add_u64 v[166:167], v[138:139], 0, v[178:179]
	v_lshl_add_u64 v[174:175], v[140:141], 0, v[178:179]
	global_load_dwordx4 v[162:165], v[166:167], off offset:16
	s_nop 0
	global_load_dwordx4 v[166:169], v[166:167], off
	s_nop 0
	global_load_dwordx4 v[170:173], v[174:175], off offset:16
	s_nop 0
	global_load_dwordx4 v[174:177], v[174:175], off
	s_cmp_lt_i32 s28, 4
	s_cselect_b64 vcc, -1, 0
	v_mov_b32_e32 v148, 0x3e38aa3b
	v_cndmask_b32_e32 v148, 1.0, v148, vcc
	s_lshl_b32 s0, s28, 8
	s_ashr_i32 s1, s0, 31
	s_movk_i32 s15, 0x1800
	s_lshl_b64 s[28:29], s[0:1], 1
	s_waitcnt vmcnt(0)
	v_pk_mul_f32 v[206:207], v[114:115], v[170:171]
	v_pk_mul_f32 v[198:199], v[118:119], v[174:175]
	v_pk_fma_f32 v[206:207], v[122:123], v[162:163], v[206:207] neg_lo:[0,0,1] neg_hi:[0,0,1]
	v_pk_fma_f32 v[198:199], v[126:127], v[166:167], v[198:199] neg_lo:[0,0,1] neg_hi:[0,0,1]
	v_pk_mul_f32 v[126:127], v[126:127], v[174:175]
	v_pk_mul_f32 v[122:123], v[122:123], v[170:171]
	v_pk_fma_f32 v[118:119], v[118:119], v[166:167], v[126:127]
	v_pk_mul_f32 v[202:203], v[116:117], v[172:173]
	v_pk_mul_f32 v[126:127], v[148:149], v[118:119] op_sel_hi:[0,1]
	v_pk_mul_f32 v[118:119], v[124:125], v[172:173]
	v_pk_fma_f32 v[114:115], v[114:115], v[162:163], v[122:123]
	v_pk_fma_f32 v[202:203], v[124:125], v[164:165], v[202:203] neg_lo:[0,0,1] neg_hi:[0,0,1]
	v_pk_fma_f32 v[116:117], v[116:117], v[164:165], v[118:119]
	v_pk_mul_f32 v[124:125], v[148:149], v[114:115] op_sel_hi:[0,1]
	v_mov_b64_e32 v[114:115], s[10:11]
	v_pk_mul_f32 v[122:123], v[148:149], v[116:117] op_sel_hi:[0,1]
	v_mad_i64_i32 v[116:117], s[16:17], v147, s15, v[114:115]
	v_pk_mul_f32 v[196:197], v[120:121], v[176:177]
	v_lshl_add_u64 v[116:117], v[116:117], 0, s[28:29]
	v_pk_fma_f32 v[196:197], v[128:129], v[168:169], v[196:197] neg_lo:[0,0,1] neg_hi:[0,0,1]
	v_pk_mul_f32 v[128:129], v[128:129], v[176:177]
	v_lshl_add_u64 v[116:117], v[116:117], 0, s[82:83]
	v_mov_b32_e32 v147, v179
	v_pk_mul_f32 v[198:199], v[148:149], v[198:199] op_sel_hi:[0,1]
	v_pk_fma_f32 v[120:121], v[120:121], v[168:169], v[128:129]
	v_lshl_add_u64 v[128:129], v[116:117], 0, v[146:147]
	v_cvt_pk_bf16_f32 v116, v198, v199
	v_pk_mul_f32 v[196:197], v[148:149], v[196:197] op_sel_hi:[0,1]
	v_pk_mul_f32 v[202:203], v[148:149], v[202:203] op_sel_hi:[0,1]
	v_pk_mul_f32 v[206:207], v[148:149], v[206:207] op_sel_hi:[0,1]
	v_cvt_pk_bf16_f32 v117, v196, v197
	v_cvt_pk_bf16_f32 v118, v206, v207
	v_cvt_pk_bf16_f32 v119, v202, v203
	global_store_dwordx4 v[128:129], v[116:119], off sc1
	v_pk_mul_f32 v[120:121], v[148:149], v[120:121] op_sel_hi:[0,1]
	s_nop 0
	v_cvt_pk_bf16_f32 v116, v126, v127
	v_cvt_pk_bf16_f32 v117, v120, v121
	v_cvt_pk_bf16_f32 v118, v124, v125
	v_cvt_pk_bf16_f32 v119, v122, v123
	global_store_dwordx4 v[128:129], v[116:119], off offset:64 sc1
	s_nop 1
	v_lshlrev_b32_e32 v116, 7, v160
	v_and_b32_e32 v178, 0x3ef80, v116
	v_lshl_add_u64 v[120:121], v[138:139], 0, v[178:179]
	v_lshl_add_u64 v[128:129], v[140:141], 0, v[178:179]
	global_load_dwordx4 v[116:119], v[120:121], off offset:16
	s_nop 0
	global_load_dwordx4 v[120:123], v[120:121], off
	s_nop 0
	global_load_dwordx4 v[124:127], v[128:129], off offset:16
	global_load_dwordx4 v[162:165], v[128:129], off
	s_waitcnt vmcnt(1)
	v_pk_mul_f32 v[170:171], v[98:99], v[124:125]
	v_pk_mul_f32 v[168:169], v[100:101], v[126:127]
	v_pk_fma_f32 v[170:171], v[106:107], v[116:117], v[170:171] neg_lo:[0,0,1] neg_hi:[0,0,1]
	v_pk_mul_f32 v[106:107], v[106:107], v[124:125]
	v_pk_fma_f32 v[168:169], v[108:109], v[118:119], v[168:169] neg_lo:[0,0,1] neg_hi:[0,0,1]
	v_pk_mul_f32 v[108:109], v[108:109], v[126:127]
	v_pk_fma_f32 v[98:99], v[98:99], v[116:117], v[106:107]
	v_pk_fma_f32 v[100:101], v[100:101], v[118:119], v[108:109]
	v_pk_mul_f32 v[108:109], v[148:149], v[98:99] op_sel_hi:[0,1]
	v_mad_i64_i32 v[98:99], s[0:1], v160, s15, v[114:115]
	s_waitcnt vmcnt(0)
	v_pk_mul_f32 v[166:167], v[102:103], v[162:163]
	v_lshl_add_u64 v[98:99], v[98:99], 0, s[28:29]
	v_pk_mul_f32 v[128:129], v[104:105], v[164:165]
	v_pk_fma_f32 v[166:167], v[110:111], v[120:121], v[166:167] neg_lo:[0,0,1] neg_hi:[0,0,1]
	v_pk_mul_f32 v[110:111], v[110:111], v[162:163]
	v_lshl_add_u64 v[98:99], v[98:99], 0, s[82:83]
	v_pk_fma_f32 v[128:129], v[112:113], v[122:123], v[128:129] neg_lo:[0,0,1] neg_hi:[0,0,1]
	v_pk_mul_f32 v[166:167], v[148:149], v[166:167] op_sel_hi:[0,1]
	v_pk_mul_f32 v[112:113], v[112:113], v[164:165]
	v_pk_fma_f32 v[102:103], v[102:103], v[120:121], v[110:111]
	v_lshl_add_u64 v[110:111], v[98:99], 0, v[146:147]
	v_cvt_pk_bf16_f32 v98, v166, v167
	v_pk_mul_f32 v[128:129], v[148:149], v[128:129] op_sel_hi:[0,1]
	v_pk_mul_f32 v[168:169], v[148:149], v[168:169] op_sel_hi:[0,1]
	v_pk_mul_f32 v[170:171], v[148:149], v[170:171] op_sel_hi:[0,1]
	v_pk_fma_f32 v[104:105], v[104:105], v[122:123], v[112:113]
	v_pk_mul_f32 v[102:103], v[148:149], v[102:103] op_sel_hi:[0,1]
	v_pk_mul_f32 v[106:107], v[148:149], v[100:101] op_sel_hi:[0,1]
	v_cvt_pk_bf16_f32 v99, v128, v129
	v_cvt_pk_bf16_f32 v100, v170, v171
	v_cvt_pk_bf16_f32 v101, v168, v169
	global_store_dwordx4 v[110:111], v[98:101], off sc1
	v_pk_mul_f32 v[104:105], v[148:149], v[104:105] op_sel_hi:[0,1]
	s_nop 0
	v_cvt_pk_bf16_f32 v98, v102, v103
	v_cvt_pk_bf16_f32 v99, v104, v105
	v_cvt_pk_bf16_f32 v100, v108, v109
	v_cvt_pk_bf16_f32 v101, v106, v107
	global_store_dwordx4 v[110:111], v[98:101], off offset:64 sc1
	s_nop 1
	v_lshlrev_b32_e32 v98, 7, v159
	v_and_b32_e32 v178, 0x3f780, v98
	v_lshl_add_u64 v[102:103], v[138:139], 0, v[178:179]
	v_lshl_add_u64 v[110:111], v[140:141], 0, v[178:179]
	global_load_dwordx4 v[98:101], v[102:103], off offset:16
	s_nop 0
	global_load_dwordx4 v[102:105], v[102:103], off
	s_nop 0
	global_load_dwordx4 v[106:109], v[110:111], off offset:16
	s_nop 0
	global_load_dwordx4 v[110:113], v[110:111], off
	s_waitcnt vmcnt(1)
	v_pk_mul_f32 v[122:123], v[82:83], v[106:107]
	v_pk_mul_f32 v[120:121], v[84:85], v[108:109]
	v_pk_fma_f32 v[122:123], v[90:91], v[98:99], v[122:123] neg_lo:[0,0,1] neg_hi:[0,0,1]
	v_pk_mul_f32 v[90:91], v[90:91], v[106:107]
	v_pk_fma_f32 v[120:121], v[92:93], v[100:101], v[120:121] neg_lo:[0,0,1] neg_hi:[0,0,1]
	v_pk_mul_f32 v[92:93], v[92:93], v[108:109]
	v_pk_fma_f32 v[82:83], v[82:83], v[98:99], v[90:91]
	v_pk_fma_f32 v[84:85], v[84:85], v[100:101], v[92:93]
	v_pk_mul_f32 v[92:93], v[148:149], v[82:83] op_sel_hi:[0,1]
	v_mad_i64_i32 v[82:83], s[0:1], v159, s15, v[114:115]
	s_waitcnt vmcnt(0)
	v_pk_mul_f32 v[118:119], v[86:87], v[110:111]
	v_lshl_add_u64 v[82:83], v[82:83], 0, s[28:29]
	v_pk_mul_f32 v[116:117], v[88:89], v[112:113]
	v_pk_fma_f32 v[118:119], v[94:95], v[102:103], v[118:119] neg_lo:[0,0,1] neg_hi:[0,0,1]
	v_pk_mul_f32 v[94:95], v[94:95], v[110:111]
	v_lshl_add_u64 v[82:83], v[82:83], 0, s[82:83]
	v_pk_fma_f32 v[116:117], v[96:97], v[104:105], v[116:117] neg_lo:[0,0,1] neg_hi:[0,0,1]
	v_pk_mul_f32 v[118:119], v[148:149], v[118:119] op_sel_hi:[0,1]
	v_pk_mul_f32 v[96:97], v[96:97], v[112:113]
	v_pk_fma_f32 v[86:87], v[86:87], v[102:103], v[94:95]
	v_lshl_add_u64 v[94:95], v[82:83], 0, v[146:147]
	v_cvt_pk_bf16_f32 v82, v118, v119
	v_pk_mul_f32 v[116:117], v[148:149], v[116:117] op_sel_hi:[0,1]
	v_pk_mul_f32 v[120:121], v[148:149], v[120:121] op_sel_hi:[0,1]
	v_pk_mul_f32 v[122:123], v[148:149], v[122:123] op_sel_hi:[0,1]
	v_pk_fma_f32 v[88:89], v[88:89], v[104:105], v[96:97]
	v_pk_mul_f32 v[86:87], v[148:149], v[86:87] op_sel_hi:[0,1]
	v_pk_mul_f32 v[90:91], v[148:149], v[84:85] op_sel_hi:[0,1]
	v_cvt_pk_bf16_f32 v83, v116, v117
	v_cvt_pk_bf16_f32 v84, v122, v123
	v_cvt_pk_bf16_f32 v85, v120, v121
	global_store_dwordx4 v[94:95], v[82:85], off sc1
	v_pk_mul_f32 v[88:89], v[148:149], v[88:89] op_sel_hi:[0,1]
	s_nop 0
	v_cvt_pk_bf16_f32 v82, v86, v87
	v_cvt_pk_bf16_f32 v83, v88, v89
	v_cvt_pk_bf16_f32 v84, v92, v93
	v_cvt_pk_bf16_f32 v85, v90, v91
	global_store_dwordx4 v[94:95], v[82:85], off offset:64 sc1
	s_nop 1
	v_lshlrev_b32_e32 v82, 7, v158
	v_and_b32_e32 v178, 0x3ff80, v82
	v_lshl_add_u64 v[86:87], v[138:139], 0, v[178:179]
	v_lshl_add_u64 v[94:95], v[140:141], 0, v[178:179]
	global_load_dwordx4 v[82:85], v[86:87], off offset:16
	s_nop 0
	global_load_dwordx4 v[86:89], v[86:87], off
	s_nop 0
	global_load_dwordx4 v[90:93], v[94:95], off offset:16
	s_nop 0
	global_load_dwordx4 v[94:97], v[94:95], off
	s_waitcnt vmcnt(1)
	v_pk_mul_f32 v[104:105], v[66:67], v[90:91]
	v_pk_mul_f32 v[102:103], v[68:69], v[92:93]
	v_pk_fma_f32 v[104:105], v[74:75], v[82:83], v[104:105] neg_lo:[0,0,1] neg_hi:[0,0,1]
	v_pk_mul_f32 v[74:75], v[74:75], v[90:91]
	v_pk_fma_f32 v[102:103], v[76:77], v[84:85], v[102:103] neg_lo:[0,0,1] neg_hi:[0,0,1]
	v_pk_mul_f32 v[76:77], v[76:77], v[92:93]
	v_pk_fma_f32 v[66:67], v[66:67], v[82:83], v[74:75]
	v_pk_fma_f32 v[68:69], v[68:69], v[84:85], v[76:77]
	v_pk_mul_f32 v[76:77], v[148:149], v[66:67] op_sel_hi:[0,1]
	v_mad_i64_i32 v[66:67], s[0:1], v158, s15, v[114:115]
	s_waitcnt vmcnt(0)
	v_pk_mul_f32 v[100:101], v[70:71], v[94:95]
	v_lshl_add_u64 v[66:67], v[66:67], 0, s[28:29]
	v_pk_mul_f32 v[98:99], v[72:73], v[96:97]
	v_pk_fma_f32 v[100:101], v[78:79], v[86:87], v[100:101] neg_lo:[0,0,1] neg_hi:[0,0,1]
	v_pk_mul_f32 v[78:79], v[78:79], v[94:95]
	v_lshl_add_u64 v[66:67], v[66:67], 0, s[82:83]
	v_pk_fma_f32 v[98:99], v[80:81], v[88:89], v[98:99] neg_lo:[0,0,1] neg_hi:[0,0,1]
	v_pk_mul_f32 v[100:101], v[148:149], v[100:101] op_sel_hi:[0,1]
	v_pk_mul_f32 v[80:81], v[80:81], v[96:97]
	v_pk_fma_f32 v[70:71], v[70:71], v[86:87], v[78:79]
	v_lshl_add_u64 v[78:79], v[66:67], 0, v[146:147]
	v_cvt_pk_bf16_f32 v66, v100, v101
	v_pk_mul_f32 v[98:99], v[148:149], v[98:99] op_sel_hi:[0,1]
	v_pk_mul_f32 v[102:103], v[148:149], v[102:103] op_sel_hi:[0,1]
	v_pk_mul_f32 v[104:105], v[148:149], v[104:105] op_sel_hi:[0,1]
	v_pk_fma_f32 v[72:73], v[72:73], v[88:89], v[80:81]
	v_pk_mul_f32 v[70:71], v[148:149], v[70:71] op_sel_hi:[0,1]
	v_pk_mul_f32 v[74:75], v[148:149], v[68:69] op_sel_hi:[0,1]
	v_cvt_pk_bf16_f32 v67, v98, v99
	v_cvt_pk_bf16_f32 v68, v104, v105
	v_cvt_pk_bf16_f32 v69, v102, v103
	global_store_dwordx4 v[78:79], v[66:69], off sc1
	v_pk_mul_f32 v[72:73], v[148:149], v[72:73] op_sel_hi:[0,1]
	s_nop 0
	v_cvt_pk_bf16_f32 v66, v70, v71
	v_cvt_pk_bf16_f32 v67, v72, v73
	v_cvt_pk_bf16_f32 v68, v76, v77
	v_cvt_pk_bf16_f32 v69, v74, v75
	global_store_dwordx4 v[78:79], v[66:69], off offset:64 sc1
	s_nop 1
	v_lshlrev_b32_e32 v66, 7, v157
	v_and_b32_e32 v178, 0x3e780, v66
	v_lshl_add_u64 v[70:71], v[138:139], 0, v[178:179]
	v_lshl_add_u64 v[78:79], v[140:141], 0, v[178:179]
	global_load_dwordx4 v[66:69], v[70:71], off offset:16
	s_nop 0
	global_load_dwordx4 v[70:73], v[70:71], off
	s_nop 0
	global_load_dwordx4 v[74:77], v[78:79], off offset:16
	s_nop 0
	global_load_dwordx4 v[78:81], v[78:79], off
	s_waitcnt vmcnt(1)
	v_pk_mul_f32 v[88:89], v[50:51], v[74:75]
	v_pk_mul_f32 v[86:87], v[52:53], v[76:77]
	v_pk_fma_f32 v[88:89], v[58:59], v[66:67], v[88:89] neg_lo:[0,0,1] neg_hi:[0,0,1]
	v_pk_mul_f32 v[58:59], v[58:59], v[74:75]
	v_pk_fma_f32 v[86:87], v[60:61], v[68:69], v[86:87] neg_lo:[0,0,1] neg_hi:[0,0,1]
	v_pk_mul_f32 v[60:61], v[60:61], v[76:77]
	v_pk_fma_f32 v[50:51], v[50:51], v[66:67], v[58:59]
	v_pk_fma_f32 v[52:53], v[52:53], v[68:69], v[60:61]
	v_pk_mul_f32 v[60:61], v[148:149], v[50:51] op_sel_hi:[0,1]
	v_mad_i64_i32 v[50:51], s[0:1], v157, s15, v[114:115]
	s_waitcnt vmcnt(0)
	v_pk_mul_f32 v[84:85], v[54:55], v[78:79]
	v_lshl_add_u64 v[50:51], v[50:51], 0, s[28:29]
	v_pk_mul_f32 v[82:83], v[56:57], v[80:81]
	v_pk_fma_f32 v[84:85], v[62:63], v[70:71], v[84:85] neg_lo:[0,0,1] neg_hi:[0,0,1]
	v_pk_mul_f32 v[62:63], v[62:63], v[78:79]
	v_lshl_add_u64 v[50:51], v[50:51], 0, s[82:83]
	v_pk_fma_f32 v[82:83], v[64:65], v[72:73], v[82:83] neg_lo:[0,0,1] neg_hi:[0,0,1]
	v_pk_mul_f32 v[84:85], v[148:149], v[84:85] op_sel_hi:[0,1]
	v_pk_mul_f32 v[64:65], v[64:65], v[80:81]
	v_pk_fma_f32 v[54:55], v[54:55], v[70:71], v[62:63]
	v_lshl_add_u64 v[62:63], v[50:51], 0, v[146:147]
	v_cvt_pk_bf16_f32 v50, v84, v85
	v_pk_mul_f32 v[82:83], v[148:149], v[82:83] op_sel_hi:[0,1]
	v_pk_mul_f32 v[86:87], v[148:149], v[86:87] op_sel_hi:[0,1]
	v_pk_mul_f32 v[88:89], v[148:149], v[88:89] op_sel_hi:[0,1]
	v_pk_fma_f32 v[56:57], v[56:57], v[72:73], v[64:65]
	v_pk_mul_f32 v[54:55], v[148:149], v[54:55] op_sel_hi:[0,1]
	v_pk_mul_f32 v[58:59], v[148:149], v[52:53] op_sel_hi:[0,1]
	v_cvt_pk_bf16_f32 v51, v82, v83
	v_cvt_pk_bf16_f32 v52, v88, v89
	v_cvt_pk_bf16_f32 v53, v86, v87
	global_store_dwordx4 v[62:63], v[50:53], off sc1
	v_pk_mul_f32 v[56:57], v[148:149], v[56:57] op_sel_hi:[0,1]
	s_nop 0
	v_cvt_pk_bf16_f32 v50, v54, v55
	v_cvt_pk_bf16_f32 v51, v56, v57
	v_cvt_pk_bf16_f32 v52, v60, v61
	v_cvt_pk_bf16_f32 v53, v58, v59
	global_store_dwordx4 v[62:63], v[50:53], off offset:64 sc1
	s_nop 1
	v_lshlrev_b32_e32 v50, 7, v156
	v_and_b32_e32 v178, 0x3ef80, v50
	v_lshl_add_u64 v[54:55], v[138:139], 0, v[178:179]
	v_lshl_add_u64 v[62:63], v[140:141], 0, v[178:179]
	global_load_dwordx4 v[50:53], v[54:55], off offset:16
	s_nop 0
	global_load_dwordx4 v[54:57], v[54:55], off
	s_nop 0
	global_load_dwordx4 v[58:61], v[62:63], off offset:16
	s_nop 0
	global_load_dwordx4 v[62:65], v[62:63], off
	s_waitcnt vmcnt(1)
	v_pk_mul_f32 v[72:73], v[34:35], v[58:59]
	v_pk_mul_f32 v[70:71], v[36:37], v[60:61]
	v_pk_fma_f32 v[72:73], v[42:43], v[50:51], v[72:73] neg_lo:[0,0,1] neg_hi:[0,0,1]
	v_pk_mul_f32 v[42:43], v[42:43], v[58:59]
	v_pk_fma_f32 v[70:71], v[44:45], v[52:53], v[70:71] neg_lo:[0,0,1] neg_hi:[0,0,1]
	v_pk_mul_f32 v[44:45], v[44:45], v[60:61]
	v_pk_fma_f32 v[34:35], v[34:35], v[50:51], v[42:43]
	v_pk_fma_f32 v[36:37], v[36:37], v[52:53], v[44:45]
	v_pk_mul_f32 v[44:45], v[148:149], v[34:35] op_sel_hi:[0,1]
	v_mad_i64_i32 v[34:35], s[0:1], v156, s15, v[114:115]
	s_waitcnt vmcnt(0)
	v_pk_mul_f32 v[68:69], v[38:39], v[62:63]
	v_lshl_add_u64 v[34:35], v[34:35], 0, s[28:29]
	v_pk_mul_f32 v[66:67], v[40:41], v[64:65]
	v_pk_fma_f32 v[68:69], v[46:47], v[54:55], v[68:69] neg_lo:[0,0,1] neg_hi:[0,0,1]
	v_pk_mul_f32 v[46:47], v[46:47], v[62:63]
	v_lshl_add_u64 v[34:35], v[34:35], 0, s[82:83]
	v_pk_fma_f32 v[66:67], v[48:49], v[56:57], v[66:67] neg_lo:[0,0,1] neg_hi:[0,0,1]
	v_pk_mul_f32 v[68:69], v[148:149], v[68:69] op_sel_hi:[0,1]
	v_pk_mul_f32 v[48:49], v[48:49], v[64:65]
	v_pk_fma_f32 v[38:39], v[38:39], v[54:55], v[46:47]
	v_lshl_add_u64 v[46:47], v[34:35], 0, v[146:147]
	v_cvt_pk_bf16_f32 v34, v68, v69
	v_pk_mul_f32 v[66:67], v[148:149], v[66:67] op_sel_hi:[0,1]
	v_pk_mul_f32 v[70:71], v[148:149], v[70:71] op_sel_hi:[0,1]
	v_pk_mul_f32 v[72:73], v[148:149], v[72:73] op_sel_hi:[0,1]
	v_pk_fma_f32 v[40:41], v[40:41], v[56:57], v[48:49]
	v_pk_mul_f32 v[38:39], v[148:149], v[38:39] op_sel_hi:[0,1]
	v_pk_mul_f32 v[42:43], v[148:149], v[36:37] op_sel_hi:[0,1]
	v_cvt_pk_bf16_f32 v35, v66, v67
	v_cvt_pk_bf16_f32 v36, v72, v73
	v_cvt_pk_bf16_f32 v37, v70, v71
	global_store_dwordx4 v[46:47], v[34:37], off sc1
	v_pk_mul_f32 v[40:41], v[148:149], v[40:41] op_sel_hi:[0,1]
	s_nop 0
	v_cvt_pk_bf16_f32 v34, v38, v39
	v_cvt_pk_bf16_f32 v35, v40, v41
	v_cvt_pk_bf16_f32 v36, v44, v45
	v_cvt_pk_bf16_f32 v37, v42, v43
	global_store_dwordx4 v[46:47], v[34:37], off offset:64 sc1
	s_nop 1
	v_lshlrev_b32_e32 v34, 7, v155
	v_and_b32_e32 v178, 0x3f780, v34
	v_lshl_add_u64 v[38:39], v[138:139], 0, v[178:179]
	v_lshl_add_u64 v[46:47], v[140:141], 0, v[178:179]
	global_load_dwordx4 v[34:37], v[38:39], off offset:16
	s_nop 0
	global_load_dwordx4 v[38:41], v[38:39], off
	s_nop 0
	global_load_dwordx4 v[42:45], v[46:47], off offset:16
	s_nop 0
	global_load_dwordx4 v[46:49], v[46:47], off
	s_waitcnt vmcnt(1)
	v_pk_mul_f32 v[56:57], v[18:19], v[42:43]
	v_pk_mul_f32 v[54:55], v[20:21], v[44:45]
	v_pk_fma_f32 v[56:57], v[26:27], v[34:35], v[56:57] neg_lo:[0,0,1] neg_hi:[0,0,1]
	v_pk_mul_f32 v[26:27], v[26:27], v[42:43]
	v_pk_fma_f32 v[54:55], v[28:29], v[36:37], v[54:55] neg_lo:[0,0,1] neg_hi:[0,0,1]
	v_pk_mul_f32 v[28:29], v[28:29], v[44:45]
	v_pk_fma_f32 v[18:19], v[18:19], v[34:35], v[26:27]
	v_pk_fma_f32 v[20:21], v[20:21], v[36:37], v[28:29]
	v_pk_mul_f32 v[28:29], v[148:149], v[18:19] op_sel_hi:[0,1]
	v_mad_i64_i32 v[18:19], s[0:1], v155, s15, v[114:115]
	s_waitcnt vmcnt(0)
	v_pk_mul_f32 v[52:53], v[22:23], v[46:47]
	v_lshl_add_u64 v[18:19], v[18:19], 0, s[28:29]
	v_pk_mul_f32 v[50:51], v[24:25], v[48:49]
	v_pk_fma_f32 v[52:53], v[30:31], v[38:39], v[52:53] neg_lo:[0,0,1] neg_hi:[0,0,1]
	v_pk_mul_f32 v[30:31], v[30:31], v[46:47]
	v_lshl_add_u64 v[18:19], v[18:19], 0, s[82:83]
	v_pk_fma_f32 v[50:51], v[32:33], v[40:41], v[50:51] neg_lo:[0,0,1] neg_hi:[0,0,1]
	v_pk_mul_f32 v[52:53], v[148:149], v[52:53] op_sel_hi:[0,1]
	v_pk_mul_f32 v[32:33], v[32:33], v[48:49]
	v_pk_fma_f32 v[22:23], v[22:23], v[38:39], v[30:31]
	v_lshl_add_u64 v[30:31], v[18:19], 0, v[146:147]
	v_cvt_pk_bf16_f32 v18, v52, v53
	v_pk_mul_f32 v[50:51], v[148:149], v[50:51] op_sel_hi:[0,1]
	v_pk_mul_f32 v[54:55], v[148:149], v[54:55] op_sel_hi:[0,1]
	v_pk_mul_f32 v[56:57], v[148:149], v[56:57] op_sel_hi:[0,1]
	v_pk_fma_f32 v[24:25], v[24:25], v[40:41], v[32:33]
	v_pk_mul_f32 v[22:23], v[148:149], v[22:23] op_sel_hi:[0,1]
	v_pk_mul_f32 v[26:27], v[148:149], v[20:21] op_sel_hi:[0,1]
	v_cvt_pk_bf16_f32 v19, v50, v51
	v_cvt_pk_bf16_f32 v20, v56, v57
	v_cvt_pk_bf16_f32 v21, v54, v55
	global_store_dwordx4 v[30:31], v[18:21], off sc1
	v_pk_mul_f32 v[24:25], v[148:149], v[24:25] op_sel_hi:[0,1]
	s_nop 0
	v_cvt_pk_bf16_f32 v18, v22, v23
	v_cvt_pk_bf16_f32 v19, v24, v25
	v_cvt_pk_bf16_f32 v20, v28, v29
	v_cvt_pk_bf16_f32 v21, v26, v27
	global_store_dwordx4 v[30:31], v[18:21], off offset:64 sc1
	s_nop 1
	v_lshlrev_b32_e32 v18, 7, v154
	v_and_b32_e32 v178, 0x3ff80, v18
	v_lshl_add_u64 v[18:19], v[138:139], 0, v[178:179]
	global_load_dwordx4 v[22:25], v[18:19], off offset:16
	global_load_dwordx4 v[26:29], v[18:19], off
	v_lshl_add_u64 v[18:19], v[140:141], 0, v[178:179]
	global_load_dwordx4 v[30:33], v[18:19], off offset:16
	global_load_dwordx4 v[34:37], v[18:19], off
	s_waitcnt vmcnt(1)
	v_pk_mul_f32 v[40:41], v[2:3], v[30:31]
	s_waitcnt vmcnt(0)
	v_pk_mul_f32 v[20:21], v[6:7], v[34:35]
	v_pk_fma_f32 v[40:41], v[10:11], v[22:23], v[40:41] neg_lo:[0,0,1] neg_hi:[0,0,1]
	v_pk_fma_f32 v[20:21], v[14:15], v[26:27], v[20:21] neg_lo:[0,0,1] neg_hi:[0,0,1]
	v_pk_mul_f32 v[10:11], v[10:11], v[30:31]
	v_pk_mul_f32 v[38:39], v[148:149], v[20:21] op_sel_hi:[0,1]
	v_pk_mul_f32 v[20:21], v[4:5], v[32:33]
	v_pk_fma_f32 v[10:11], v[2:3], v[22:23], v[10:11]
	v_pk_fma_f32 v[20:21], v[12:13], v[24:25], v[20:21] neg_lo:[0,0,1] neg_hi:[0,0,1]
	v_pk_mul_f32 v[12:13], v[12:13], v[32:33]
	v_pk_mul_f32 v[18:19], v[8:9], v[36:37]
	v_pk_fma_f32 v[4:5], v[4:5], v[24:25], v[12:13]
	v_pk_fma_f32 v[18:19], v[16:17], v[28:29], v[18:19] neg_lo:[0,0,1] neg_hi:[0,0,1]
	v_pk_mul_f32 v[2:3], v[148:149], v[4:5] op_sel_hi:[0,1]
	v_pk_mul_f32 v[4:5], v[148:149], v[10:11] op_sel_hi:[0,1]
	v_mad_i64_i32 v[10:11], s[0:1], v154, s15, v[114:115]
	v_pk_mul_f32 v[16:17], v[16:17], v[36:37]
	v_pk_mul_f32 v[14:15], v[14:15], v[34:35]
	v_lshl_add_u64 v[10:11], v[10:11], 0, s[28:29]
	v_pk_fma_f32 v[8:9], v[8:9], v[28:29], v[16:17]
	v_pk_fma_f32 v[14:15], v[6:7], v[26:27], v[14:15]
	v_lshl_add_u64 v[10:11], v[10:11], 0, s[82:83]
	v_pk_mul_f32 v[18:19], v[148:149], v[18:19] op_sel_hi:[0,1]
	v_pk_mul_f32 v[6:7], v[148:149], v[8:9] op_sel_hi:[0,1]
	v_pk_mul_f32 v[8:9], v[148:149], v[14:15] op_sel_hi:[0,1]
	v_lshl_add_u64 v[14:15], v[10:11], 0, v[146:147]
	v_cvt_pk_bf16_f32 v10, v38, v39
	v_cvt_pk_bf16_f32 v11, v18, v19
	v_pk_mul_f32 v[20:21], v[148:149], v[20:21] op_sel_hi:[0,1]
	v_pk_mul_f32 v[40:41], v[148:149], v[40:41] op_sel_hi:[0,1]
	v_cvt_pk_bf16_f32 v12, v40, v41
	v_cvt_pk_bf16_f32 v13, v20, v21
	global_store_dwordx4 v[14:15], v[10:13], off sc1
	v_cvt_pk_bf16_f32 v8, v8, v9
	v_cvt_pk_bf16_f32 v9, v6, v7
	s_nop 1
	v_cvt_pk_bf16_f32 v10, v4, v5
	v_cvt_pk_bf16_f32 v11, v2, v3
	global_store_dwordx4 v[14:15], v[8:11], off offset:64 sc1
	s_andn2_b64 vcc, exec, s[4:5]
	s_mov_b64 s[0:1], -1
	s_cbranch_vccnz .LBB0_211

.LBB0_281:
	s_lshl_b32 s0, s17, 1
	s_lshr_b32 s1, s21, 6
	s_and_b32 s29, s0, 0x700
	s_and_b32 s0, s21, 3
	s_and_b32 s1, s1, 0x1fffffc
	s_or_b32 s0, s1, s0
	v_mov_b32_e32 v18, v0
	s_lshl_b32 s1, s21, 6
	v_readfirstlane_b32 s24, v18
	s_lshl_b32 s0, s0, 7
	s_lshr_b32 s23, s24, 6
	s_ashr_i32 s25, s24, 8
	s_bfe_u32 s28, s24, 0x20006
	s_and_b32 s4, s1, 0x3800
	s_ashr_i32 s1, s0, 31
	s_add_u32 s0, s0, s4
	s_addc_u32 s19, s1, 0
	s_lshl_b32 s1, s28, 5
	v_and_b32_e32 v164, 31, v18
	s_or_b32 s18, s0, s1
	v_or_b32_e32 v4, s18, v164
	v_mov_b64_e32 v[2:3], s[10:11]
	s_movk_i32 s39, 0x1800
	v_mad_u64_u32 v[2:3], s[0:1], v4, s39, v[2:3]
	s_lshl_b32 s0, s21, 5
	v_mov_b32_e32 v4, 0x1800
	s_and_b32 s22, s0, 0x380
	v_mad_i32_i24 v3, s19, v4, v3
	s_lshl_b32 s82, s22, 1
	s_lshl_b32 s0, s25, 6
	v_bfe_u32 v173, v18, 5, 1
	v_lshl_add_u64 v[2:3], v[2:3], 0, s[82:83]
	s_ashr_i32 s1, s0, 31
	v_lshl_add_u64 v[2:3], s[0:1], 1, v[2:3]
	v_lshlrev_b32_e32 v178, 4, v173
	v_lshl_add_u64 v[2:3], v[2:3], 0, v[178:179]
	v_ashrrev_i32_e32 v19, 4, v18
	global_load_dwordx4 v[126:129], v[2:3], off
	global_load_dwordx4 v[122:125], v[2:3], off offset:32
	global_load_dwordx4 v[118:121], v[2:3], off offset:64
	global_load_dwordx4 v[114:117], v[2:3], off offset:96
	v_and_b32_e32 v3, 0xfffff0, v19
	v_lshlrev_b32_e32 v4, 1, v19
	v_lshlrev_b32_e32 v2, 3, v18
	v_and_or_b32 v3, v4, 8, v3
	v_and_b32_e32 v162, 0x78, v2
	v_lshrrev_b32_e32 v4, 1, v19
	v_lshrrev_b32_e32 v3, 1, v3
	v_bfe_u32 v2, v2, 5, 2
	v_and_b32_e32 v5, 3, v19
	v_or_b32_e32 v3, v3, v2
	v_and_or_b32 v4, v4, 4, v5
	v_lshlrev_b32_e32 v36, 1, v162
	v_lshlrev_b32_e32 v3, 9, v3
	v_lshlrev_b32_e32 v4, 6, v4
	v_and_b32_e32 v5, 48, v36
	v_add_u32_e32 v38, 32, v19
	v_or3_b32 v37, v3, v4, v5
	v_and_b32_e32 v3, 0xfffff0, v38
	v_lshlrev_b32_e32 v6, 1, v38
	v_and_or_b32 v3, v6, 8, v3
	v_lshrrev_b32_e32 v3, 1, v3
	s_mulk_i32 s4, 0x1800
	v_or_b32_e32 v2, v3, v2
	v_and_b32_e32 v172, 63, v18
	s_add_u32 s0, s10, s4
	v_lshlrev_b32_e32 v2, 9, v2
	v_lshlrev_b32_e32 v40, 4, v18
	s_addc_u32 s1, s11, 0
	v_or3_b32 v39, v2, v4, v5
	v_lshlrev_b32_e32 v2, 3, v172
	v_and_b32_e32 v3, 0xc0, v40
	v_lshlrev_b32_e32 v4, 1, v18
	s_add_u32 s0, s0, s82
	v_and_or_b32 v3, v2, 24, v3
	v_and_b32_e32 v4, 32, v4
	v_and_b32_e32 v2, 0x100, v2
	s_addc_u32 s1, s1, 0
	v_or3_b32 v44, v3, v4, v2
	v_mad_i64_i32 v[2:3], s[34:35], v19, s40, 0
	s_add_u32 s4, s0, 0x1000
	v_or_b32_e32 v2, v2, v162
	s_addc_u32 s5, s1, 0
	v_lshlrev_b64 v[10:11], 1, v[2:3]
	v_lshl_add_u64 v[2:3], s[4:5], 0, v[10:11]
	global_load_dwordx4 v[2:5], v[2:3], off
	v_mad_i64_i32 v[6:7], s[34:35], v38, s40, 0
	v_or_b32_e32 v6, v6, v162
	v_lshlrev_b64 v[14:15], 1, v[6:7]
	v_lshl_add_u64 v[6:7], s[4:5], 0, v[14:15]
	v_lshl_add_u64 v[10:11], s[0:1], 0, v[10:11]
	v_lshl_add_u64 v[14:15], s[0:1], 0, v[14:15]
	global_load_dwordx4 v[6:9], v[6:7], off
	v_add_u32_e32 v20, 64, v19
	global_load_dwordx4 v[10:13], v[10:11], off offset:2048
	v_add_u32_e32 v24, 0x60, v19
	global_load_dwordx4 v[14:17], v[14:15], off offset:2048
	v_mad_i64_i32 v[20:21], s[34:35], v20, s40, 0
	v_mad_i64_i32 v[24:25], s[34:35], v24, s40, 0
	v_or_b32_e32 v20, v20, v162
	v_or_b32_e32 v24, v24, v162
	v_lshlrev_b64 v[28:29], 1, v[20:21]
	v_lshlrev_b64 v[32:33], 1, v[24:25]
	v_lshl_add_u64 v[20:21], s[4:5], 0, v[28:29]
	v_lshl_add_u64 v[24:25], s[4:5], 0, v[32:33]
	v_lshl_add_u64 v[28:29], s[0:1], 0, v[28:29]
	v_lshl_add_u64 v[32:33], s[0:1], 0, v[32:33]
	v_add_u32_e32 v177, 0, v37
	global_load_dwordx4 v[20:23], v[20:21], off
	s_lshl_b32 s31, s25, 7
	global_load_dwordx4 v[24:27], v[24:25], off
	v_and_b32_e32 v46, 0xf0, v40
	global_load_dwordx4 v[28:31], v[28:29], off offset:2048
	v_lshl_add_u32 v47, v164, 8, 0
	global_load_dwordx4 v[32:35], v[32:33], off offset:2048
	s_waitcnt vmcnt(4)
	v_add_u32_e32 v185, 0, v39
	v_or_b32_e32 v45, s31, v178
	v_mov_b32_e32 v174, 0
	v_add_u32_e32 v176, 0, v44
	v_mov_b32_e32 v48, v174
	v_mov_b32_e32 v49, v174
	v_mov_b32_e32 v50, 0
	v_mov_b32_e32 v51, v174
	v_mov_b32_e32 v52, v174
	v_mov_b32_e32 v53, v174
	v_mov_b32_e32 v54, v174
	v_mov_b32_e32 v55, v174
	v_mov_b32_e32 v56, v174
	v_mov_b32_e32 v57, v174
	v_mov_b32_e32 v58, v174
	v_mov_b32_e32 v59, v174
	v_mov_b32_e32 v60, v174
	v_mov_b32_e32 v61, v174
	v_mov_b32_e32 v62, v174
	v_mov_b32_e32 v63, v174
	v_mov_b32_e32 v64, v174
	v_mov_b32_e32 v65, v174
	s_waitcnt vmcnt(7)
	ds_write_b128 v177, v[2:5]
	v_lshlrev_b32_e32 v2, 8, v19
	v_and_b32_e32 v3, 0xf0, v18
	v_bitop3_b32 v2, v36, v2, v3 bitop3:0xde
	v_add_u32_e32 v197, 0, v2
	v_lshlrev_b32_e32 v2, 8, v38
	v_bitop3_b32 v2, v36, v2, v3 bitop3:0xde
	v_add_u32_e32 v198, 0, v2
	v_bitop3_b32 v2, s31, v46, v178 bitop3:0x36
	v_add_u32_e32 v212, v47, v2
	s_waitcnt vmcnt(6)
	ds_write_b128 v185, v[6:9]
	s_waitcnt vmcnt(5)
	ds_write_b128 v197, v[10:13] offset:32768
	s_waitcnt vmcnt(4)
	ds_write_b128 v198, v[14:17] offset:32768
	s_waitcnt lgkmcnt(0)
	s_barrier
	ds_read_b128 v[2:5], v212 offset:32768
	ds_read_b128 v[36:39], v212 offset:40960
	s_waitcnt lgkmcnt(1)
	v_mfma_f32_32x32x16_bf16 v[2:17], v[2:5], v[126:129], 0
	s_waitcnt lgkmcnt(0)
	v_mfma_f32_32x32x16_bf16 v[66:81], v[36:39], v[126:129], 0
	v_bitop3_b32 v36, v45, v46, 32 bitop3:0x36
	v_add_u32_e32 v213, v47, v36
	ds_read_b128 v[36:39], v213 offset:32768
	ds_read_b128 v[40:43], v213 offset:40960
	s_waitcnt lgkmcnt(1)
	v_mfma_f32_32x32x16_bf16 v[2:17], v[36:39], v[122:125], v[2:17]
	v_bitop3_b32 v36, v45, v46, 64 bitop3:0x36
	v_add_u32_e32 v199, v47, v36
	s_waitcnt lgkmcnt(0)
	v_mfma_f32_32x32x16_bf16 v[66:81], v[40:43], v[122:125], v[66:81]
	ds_read_b128 v[36:39], v199 offset:32768
	ds_read_b128 v[40:43], v199 offset:40960
	s_waitcnt lgkmcnt(1)
	v_mfma_f32_32x32x16_bf16 v[2:17], v[36:39], v[118:121], v[2:17]
	v_bitop3_b32 v36, v45, v46, s89 bitop3:0x36
	v_add_u32_e32 v196, v47, v36
	v_mov_b32_e32 v45, v174
	v_mov_b32_e32 v46, v174
	v_mov_b32_e32 v47, v174
	s_waitcnt lgkmcnt(0)
	v_mfma_f32_32x32x16_bf16 v[66:81], v[40:43], v[118:121], v[66:81]
	ds_read_b128 v[36:39], v196 offset:32768
	ds_read_b128 v[40:43], v196 offset:40960
	s_waitcnt lgkmcnt(1)
	v_mfma_f32_32x32x16_bf16 v[2:17], v[36:39], v[114:117], v[2:17]
	v_mov_b32_e32 v36, v174
	v_mov_b32_e32 v37, v174
	v_mov_b32_e32 v38, v174
	v_mov_b32_e32 v39, v174
	s_waitcnt lgkmcnt(0)
	v_mfma_f32_32x32x16_bf16 v[66:81], v[40:43], v[114:117], v[66:81]
	s_nop 5
	s_nop 0
	s_nop 0
	v_exp_f32_e32 v217, v2
	v_add_u32_e32 v2, 0x80, v19
	v_exp_f32_e32 v222, v3
	v_mad_i64_i32 v[2:3], s[34:35], v2, s40, 0
	s_nop 0
	s_nop 0
	v_or_b32_e32 v2, v2, v162
	v_lshlrev_b64 v[2:3], 1, v[2:3]
	v_exp_f32_e32 v223, v4
	v_exp_f32_e32 v225, v5
	v_lshl_add_u64 v[4:5], s[4:5], 0, v[2:3]
	v_lshl_add_u64 v[2:3], s[0:1], 0, v[2:3]
	global_load_dwordx4 v[130:133], v[4:5], off
	global_load_dwordx4 v[138:141], v[2:3], off offset:2048
	v_add_u32_e32 v4, 0xa0, v19
	v_mad_i64_i32 v[4:5], s[34:35], v4, s40, 0
	s_nop 0
	s_nop 0
	v_or_b32_e32 v4, v4, v162
	v_lshlrev_b64 v[4:5], 1, v[4:5]
	v_exp_f32_e32 v226, v6
	v_exp_f32_e32 v227, v7
	v_lshl_add_u64 v[6:7], s[4:5], 0, v[4:5]
	v_lshl_add_u64 v[2:3], s[0:1], 0, v[4:5]
	global_load_dwordx4 v[134:137], v[6:7], off
	global_load_dwordx4 v[142:145], v[2:3], off offset:2048
	s_add_i32 s0, 0, 0x4000
	s_nop 0
	s_nop 0
	s_nop 0
	s_nop 0
	s_nop 0
	s_nop 0
	s_nop 0
	s_nop 0
	s_nop 0
	s_nop 0
	v_add_u32_e32 v175, s0, v44
	v_mad_i64_i32 v[2:3], s[0:1], v19, s39, 0
	s_nop 0
	v_exp_f32_e32 v228, v8
	v_exp_f32_e32 v229, v9
	v_exp_f32_e32 v214, v10
	v_exp_f32_e32 v215, v11
	v_exp_f32_e32 v216, v12
	v_exp_f32_e32 v218, v13
	v_exp_f32_e32 v219, v14
	v_exp_f32_e32 v220, v15
	v_exp_f32_e32 v221, v16
	v_exp_f32_e32 v224, v17
	s_bfe_u32 s0, s20, 0x3000b
	v_and_b32_e32 v4, 15, v18
	s_waitcnt vmcnt(4)
	v_mad_u64_u32 v[2:3], s[0:1], s0, v252, v[2:3]
	v_lshlrev_b32_e32 v4, 4, v4
	v_or3_b32 v2, v2, s29, v4
	s_waitcnt vmcnt(7)
	ds_write_b128 v177, v[20:23] offset:16384
	s_waitcnt vmcnt(6)
	ds_write_b128 v185, v[24:27] offset:16384
	s_waitcnt vmcnt(5)
	ds_write_b128 v197, v[28:31] offset:49152
	s_waitcnt vmcnt(4)
	ds_write_b128 v198, v[32:35] offset:49152
	v_lshl_add_u64 v[166:167], s[14:15], 0, v[2:3]
	s_mov_b32 s4, -1
	v_mov_b32_e32 v2, 0
	v_mov_b32_e32 v3, v174
	v_mov_b32_e32 v4, v174
	v_mov_b32_e32 v5, v174
	v_mov_b32_e32 v6, v174
	v_mov_b32_e32 v7, v174
	v_mov_b32_e32 v8, v174
	v_mov_b32_e32 v9, v174
	v_mov_b32_e32 v10, v174
	v_mov_b32_e32 v11, v174
	v_mov_b32_e32 v12, v174
	v_mov_b32_e32 v13, v174
	v_mov_b32_e32 v14, v174
	v_mov_b32_e32 v15, v174
	v_mov_b32_e32 v16, v174
	v_mov_b32_e32 v17, v174
	v_mov_b32_e32 v18, 0
	v_mov_b32_e32 v19, v174
	v_mov_b32_e32 v20, v174
	v_mov_b32_e32 v21, v174
	v_mov_b32_e32 v22, v174
	v_mov_b32_e32 v23, v174
	v_mov_b32_e32 v24, v174
	v_mov_b32_e32 v25, v174
	v_mov_b32_e32 v26, v174
	v_mov_b32_e32 v27, v174
	v_mov_b32_e32 v28, v174
	v_mov_b32_e32 v29, v174
	v_mov_b32_e32 v30, v174
	v_mov_b32_e32 v31, v174
	v_mov_b32_e32 v32, v174
	v_mov_b32_e32 v33, v174
	v_mov_b32_e32 v34, 0
	v_mov_b32_e32 v35, v174
	v_mov_b32_e32 v40, v174
	v_mov_b32_e32 v41, v174
	v_mov_b32_e32 v42, v174
	v_mov_b32_e32 v43, v174
	v_mov_b32_e32 v44, v174
	s_waitcnt lgkmcnt(0)
	s_barrier
	s_branch .LBB0_283
.LBB0_282:
	v_add_f32_e32 v202, v230, v231
	v_add_f32_e32 v174, v174, v202
	v_add_f32_e32 v202, v214, v215
	v_add_f32_e32 v174, v174, v202
	ds_read_b64_tr_b16 v[214:215], v175 offset:0
	ds_read_b64_tr_b16 v[216:217], v175 offset:0x800
	ds_read_b64_tr_b16 v[218:219], v175 offset:0x1000
	ds_read_b64_tr_b16 v[220:221], v175 offset:0x1800
	ds_read_b64_tr_b16 v[222:223], v175 offset:0x2000
	ds_read_b64_tr_b16 v[224:225], v175 offset:0x2800
	ds_read_b64_tr_b16 v[226:227], v175 offset:0x3000
	ds_read_b64_tr_b16 v[228:229], v175 offset:0x3800
	s_nop 0
	s_waitcnt lgkmcnt(6)
	s_mov_b64 s[34:35], 0xc0000
	v_mfma_f32_32x32x16_bf16 v[2:17], v[94:97], v[214:217], v[2:17]
	ds_read_b64_tr_b16 v[214:215], v175 offset:0x200
	ds_read_b64_tr_b16 v[216:217], v175 offset:0xa00
	s_waitcnt lgkmcnt(6)
	v_lshl_add_u64 v[166:167], v[166:167], 0, s[34:35]
	s_and_b64 vcc, exec, s[0:1]
	v_mfma_f32_32x32x16_bf16 v[2:17], v[90:93], v[218:221], v[2:17]
	ds_read_b64_tr_b16 v[218:219], v175 offset:0x1200
	ds_read_b64_tr_b16 v[220:221], v175 offset:0x1a00
	s_waitcnt lgkmcnt(6)
	s_nop 0
	v_mfma_f32_32x32x16_bf16 v[2:17], v[86:89], v[222:225], v[2:17]
	ds_read_b64_tr_b16 v[222:223], v175 offset:0x2200
	ds_read_b64_tr_b16 v[224:225], v175 offset:0x2a00
	s_waitcnt lgkmcnt(6)
	s_nop 0
	v_mfma_f32_32x32x16_bf16 v[2:17], v[82:85], v[226:229], v[2:17]
	ds_read_b64_tr_b16 v[226:227], v175 offset:0x3200
	ds_read_b64_tr_b16 v[228:229], v175 offset:0x3a00
	s_waitcnt lgkmcnt(6)
	s_nop 0
	v_mfma_f32_32x32x16_bf16 v[18:33], v[94:97], v[214:217], v[18:33]
	ds_read_b64_tr_b16 v[214:215], v175 offset:0x400
	ds_read_b64_tr_b16 v[216:217], v175 offset:0xc00
	s_waitcnt lgkmcnt(6)
	s_nop 0
	v_mfma_f32_32x32x16_bf16 v[18:33], v[90:93], v[218:221], v[18:33]
	ds_read_b64_tr_b16 v[218:219], v175 offset:0x1400
	ds_read_b64_tr_b16 v[220:221], v175 offset:0x1c00
	s_waitcnt lgkmcnt(6)
	s_nop 0
	v_mfma_f32_32x32x16_bf16 v[18:33], v[86:89], v[222:225], v[18:33]
	ds_read_b64_tr_b16 v[222:223], v175 offset:0x2400
	ds_read_b64_tr_b16 v[224:225], v175 offset:0x2c00
	s_waitcnt lgkmcnt(6)
	s_nop 0
	v_mfma_f32_32x32x16_bf16 v[18:33], v[82:85], v[226:229], v[18:33]
	ds_read_b64_tr_b16 v[226:227], v175 offset:0x3400
	ds_read_b64_tr_b16 v[228:229], v175 offset:0x3c00
	s_waitcnt lgkmcnt(6)
	s_nop 0
	v_mfma_f32_32x32x16_bf16 v[34:49], v[94:97], v[214:217], v[34:49]
	ds_read_b64_tr_b16 v[214:215], v175 offset:0x600
	ds_read_b64_tr_b16 v[216:217], v175 offset:0xe00
	s_waitcnt lgkmcnt(6)
	s_nop 0
	v_mfma_f32_32x32x16_bf16 v[34:49], v[90:93], v[218:221], v[34:49]
	ds_read_b64_tr_b16 v[218:219], v175 offset:0x1600
	ds_read_b64_tr_b16 v[220:221], v175 offset:0x1e00
	s_waitcnt lgkmcnt(6)
	s_nop 0
	v_mfma_f32_32x32x16_bf16 v[34:49], v[86:89], v[222:225], v[34:49]
	ds_read_b64_tr_b16 v[222:223], v175 offset:0x2600
	ds_read_b64_tr_b16 v[224:225], v175 offset:0x2e00
	s_waitcnt lgkmcnt(6)
	s_nop 0
	v_mfma_f32_32x32x16_bf16 v[34:49], v[82:85], v[226:229], v[34:49]
	ds_read_b64_tr_b16 v[226:227], v175 offset:0x3600
	ds_read_b64_tr_b16 v[228:229], v175 offset:0x3e00
	s_waitcnt lgkmcnt(6)
	s_waitcnt lgkmcnt(4)
	s_waitcnt lgkmcnt(2)
	s_nop 0
	s_waitcnt lgkmcnt(0)
	v_mfma_f32_32x32x16_bf16 v[50:65], v[94:97], v[214:217], v[50:65]
	s_nop 0
	s_nop 0
	s_nop 0
	s_nop 0
	v_mfma_f32_32x32x16_bf16 v[50:65], v[90:93], v[218:221], v[50:65]
	s_nop 0
	s_nop 0
	s_nop 0
	s_nop 0
	v_mfma_f32_32x32x16_bf16 v[50:65], v[86:89], v[222:225], v[50:65]
	s_nop 0
	s_nop 0
	s_nop 0
	s_nop 0
	v_mfma_f32_32x32x16_bf16 v[50:65], v[82:85], v[226:229], v[50:65]
	s_nop 0
	s_nop 0
	s_nop 0
	s_nop 0
	s_nop 0
	v_exp_f32_e32 v217, v98
	v_exp_f32_e32 v222, v99
	v_exp_f32_e32 v223, v100
	v_exp_f32_e32 v225, v101
	v_exp_f32_e32 v226, v102
	v_exp_f32_e32 v227, v103
	v_exp_f32_e32 v228, v104
	v_exp_f32_e32 v229, v105
	v_exp_f32_e32 v214, v106
	v_exp_f32_e32 v215, v107
	v_exp_f32_e32 v216, v108
	v_exp_f32_e32 v218, v109
	v_exp_f32_e32 v219, v110
	v_exp_f32_e32 v220, v111
	v_exp_f32_e32 v221, v112
	v_exp_f32_e32 v224, v113
	s_barrier
	s_waitcnt vmcnt(4)
	s_waitcnt vmcnt(3)
	ds_write_b128 v177, v[150:153] offset:16384
	s_waitcnt vmcnt(1)
	ds_write_b128 v185, v[158:161] offset:16384
	ds_write_b128 v197, v[146:149] offset:49152
	s_waitcnt vmcnt(0)
	ds_write_b128 v198, v[154:157] offset:49152
	s_waitcnt lgkmcnt(0)
	s_barrier
	s_cbranch_vccnz .LBB0_285
.LBB0_283:
	s_add_i32 s4, s4, 2
	ds_read_b128 v[82:85], v212 offset:49152
	ds_read_b128 v[86:89], v212 offset:57344
	ds_read_b128 v[146:149], v213 offset:49152
	ds_read_b128 v[150:153], v213 offset:57344
	s_nop 0
	s_waitcnt lgkmcnt(3)
	v_mfma_f32_32x32x16_bf16 v[98:113], v[82:85], v[126:129], 0
	s_nop 0
	s_nop 0
	s_nop 0
	s_nop 0
	s_waitcnt lgkmcnt(2)
	v_mfma_f32_32x32x16_bf16 v[82:97], v[86:89], v[126:129], 0
	s_nop 0
	s_nop 0
	s_nop 0
	s_waitcnt lgkmcnt(1)
	v_mfma_f32_32x32x16_bf16 v[98:113], v[146:149], v[122:125], v[98:113]
	s_nop 0
	s_nop 0
	v_exp_f32_e32 v154, v74
	s_nop 0
	v_exp_f32_e32 v155, v75
	s_waitcnt lgkmcnt(0)
	v_mfma_f32_32x32x16_bf16 v[82:97], v[150:153], v[122:125], v[82:97]
	ds_read_b128 v[146:149], v199 offset:49152
	ds_read_b128 v[150:153], v199 offset:57344
	s_nop 0
	v_exp_f32_e32 v156, v76
	s_nop 0
	v_exp_f32_e32 v157, v77
	s_waitcnt lgkmcnt(1)
	v_mfma_f32_32x32x16_bf16 v[98:113], v[146:149], v[118:121], v[98:113]
	s_nop 0
	v_exp_f32_e32 v158, v78
	s_nop 0
	v_exp_f32_e32 v159, v79
	s_waitcnt lgkmcnt(0)
	v_mfma_f32_32x32x16_bf16 v[82:97], v[150:153], v[118:121], v[82:97]
	ds_read_b128 v[146:149], v196 offset:49152
	ds_read_b128 v[150:153], v196 offset:57344
	s_nop 0
	v_exp_f32_e32 v160, v80
	v_cvt_pk_bf16_f32 v78, v154, v155
	v_exp_f32_e32 v81, v81
	v_cvt_pk_bf16_f32 v79, v156, v157
	s_waitcnt lgkmcnt(1)
	v_mfma_f32_32x32x16_bf16 v[98:113], v[146:149], v[114:117], v[98:113]
	v_exp_f32_e32 v146, v66
	v_exp_f32_e32 v147, v67
	v_exp_f32_e32 v148, v68
	v_add_f32_e32 v66, 0, v217
	v_add_f32_e32 v67, 0, v146
	v_exp_f32_e32 v149, v69
	v_add_f32_e32 v66, v222, v66
	v_add_f32_e32 v67, v147, v67
	s_waitcnt lgkmcnt(0)
	v_mfma_f32_32x32x16_bf16 v[82:97], v[150:153], v[114:117], v[82:97]
	v_exp_f32_e32 v150, v70
	v_add_f32_e32 v66, v223, v66
	v_add_f32_e32 v67, v148, v67
	v_exp_f32_e32 v151, v71
	v_add_f32_e32 v66, v225, v66
	v_add_f32_e32 v67, v149, v67
	v_exp_f32_e32 v152, v72
	v_add_f32_e32 v66, v226, v66
	v_add_f32_e32 v67, v150, v67
	v_exp_f32_e32 v153, v73
	v_add_f32_e32 v66, v227, v66
	v_add_f32_e32 v67, v151, v67
	v_cvt_pk_bf16_f32 v68, v226, v227
	v_add_f32_e32 v66, v228, v66
	v_add_f32_e32 v67, v152, v67
	v_cvt_pk_bf16_f32 v69, v228, v229
	v_add_f32_e32 v66, v229, v66
	v_add_f32_e32 v67, v153, v67
	v_cvt_pk_bf16_f32 v70, v214, v215
	v_add_f32_e32 v66, v214, v66
	v_add_f32_e32 v67, v154, v67
	v_cvt_pk_bf16_f32 v71, v216, v218
	v_add_f32_e32 v66, v215, v66
	v_add_f32_e32 v67, v155, v67
	v_cvt_pk_bf16_f32 v72, v219, v220
	v_add_f32_e32 v66, v216, v66
	v_add_f32_e32 v67, v156, v67
	v_cvt_pk_bf16_f32 v73, v221, v224
	v_add_f32_e32 v66, v218, v66
	v_add_f32_e32 v67, v157, v67
	v_cvt_pk_bf16_f32 v74, v146, v147
	v_add_f32_e32 v66, v219, v66
	v_add_f32_e32 v67, v158, v67
	v_cvt_pk_bf16_f32 v75, v148, v149
	v_add_f32_e32 v66, v220, v66
	v_add_f32_e32 v67, v159, v67
	v_cvt_pk_bf16_f32 v76, v150, v151
	v_add_f32_e32 v66, v221, v66
	v_add_f32_e32 v67, v160, v67
	v_cvt_pk_bf16_f32 v77, v152, v153
	v_add_f32_e32 v66, v224, v66
	v_add_f32_e32 v67, v81, v67
	v_cvt_pk_bf16_f32 v80, v158, v159
	v_add_f32_e32 v230, v66, v67
	v_mov_b32_e32 v231, v230
	v_cvt_pk_bf16_f32 v66, v217, v222
	v_cvt_pk_bf16_f32 v67, v223, v225
	v_cvt_pk_bf16_f32 v81, v160, v81
	v_permlane32_swap_b32_e32 v230, v231
	v_permlane32_swap_b32_e32 v66, v68
	v_permlane32_swap_b32_e32 v67, v69
	v_permlane32_swap_b32_e32 v70, v72
	v_permlane32_swap_b32_e32 v71, v73
	v_permlane32_swap_b32_e32 v74, v76
	v_permlane32_swap_b32_e32 v75, v77
	v_permlane32_swap_b32_e32 v78, v80
	v_permlane32_swap_b32_e32 v79, v81
	s_mov_b32 s0, 0xfff70000
	v_add_co_u32_e32 v146, vcc, s0, v166
	s_mov_b32 s0, 0xfffa0000
	s_nop 0
	v_addc_co_u32_e32 v147, vcc, -1, v167, vcc
	v_add_co_u32_e32 v154, vcc, s0, v166
	s_nop 1
	v_addc_co_u32_e32 v155, vcc, -1, v167, vcc
	global_load_dwordx4 v[150:153], v[146:147], off
	s_nop 0
	global_load_dwordx4 v[146:149], v[146:147], off offset:-2048
	s_nop 0
	global_load_dwordx4 v[158:161], v[154:155], off
	s_nop 0
	global_load_dwordx4 v[154:157], v[154:155], off offset:-2048
	ds_read_b64_tr_b16 v[214:215], v176 offset:0
	ds_read_b64_tr_b16 v[216:217], v176 offset:0x800
	ds_read_b64_tr_b16 v[218:219], v176 offset:0x1000
	ds_read_b64_tr_b16 v[220:221], v176 offset:0x1800
	ds_read_b64_tr_b16 v[222:223], v176 offset:0x2000
	ds_read_b64_tr_b16 v[224:225], v176 offset:0x2800
	ds_read_b64_tr_b16 v[226:227], v176 offset:0x3000
	ds_read_b64_tr_b16 v[228:229], v176 offset:0x3800
	s_nop 0
	s_waitcnt lgkmcnt(6)
	s_nop 0
	v_mfma_f32_32x32x16_bf16 v[2:17], v[66:69], v[214:217], v[2:17]
	ds_read_b64_tr_b16 v[214:215], v176 offset:0x200
	ds_read_b64_tr_b16 v[216:217], v176 offset:0xa00
	s_waitcnt lgkmcnt(6)
	s_nop 0
	v_mfma_f32_32x32x16_bf16 v[2:17], v[70:73], v[218:221], v[2:17]
	ds_read_b64_tr_b16 v[218:219], v176 offset:0x1200
	ds_read_b64_tr_b16 v[220:221], v176 offset:0x1a00
	s_waitcnt lgkmcnt(6)
	s_nop 0
	v_mfma_f32_32x32x16_bf16 v[2:17], v[74:77], v[222:225], v[2:17]
	ds_read_b64_tr_b16 v[222:223], v176 offset:0x2200
	ds_read_b64_tr_b16 v[224:225], v176 offset:0x2a00
	s_waitcnt lgkmcnt(6)
	s_nop 0
	v_mfma_f32_32x32x16_bf16 v[2:17], v[78:81], v[226:229], v[2:17]
	ds_read_b64_tr_b16 v[226:227], v176 offset:0x3200
	ds_read_b64_tr_b16 v[228:229], v176 offset:0x3a00
	s_waitcnt lgkmcnt(6)
	s_nop 0
	v_mfma_f32_32x32x16_bf16 v[18:33], v[66:69], v[214:217], v[18:33]
	ds_read_b64_tr_b16 v[214:215], v176 offset:0x400
	ds_read_b64_tr_b16 v[216:217], v176 offset:0xc00
	s_waitcnt lgkmcnt(6)
	s_nop 0
	v_mfma_f32_32x32x16_bf16 v[18:33], v[70:73], v[218:221], v[18:33]
	ds_read_b64_tr_b16 v[218:219], v176 offset:0x1400
	ds_read_b64_tr_b16 v[220:221], v176 offset:0x1c00
	s_waitcnt lgkmcnt(6)
	s_nop 0
	v_mfma_f32_32x32x16_bf16 v[18:33], v[74:77], v[222:225], v[18:33]
	ds_read_b64_tr_b16 v[222:223], v176 offset:0x2400
	ds_read_b64_tr_b16 v[224:225], v176 offset:0x2c00
	s_waitcnt lgkmcnt(6)
	s_nop 0
	v_mfma_f32_32x32x16_bf16 v[18:33], v[78:81], v[226:229], v[18:33]
	ds_read_b64_tr_b16 v[226:227], v176 offset:0x3400
	ds_read_b64_tr_b16 v[228:229], v176 offset:0x3c00
	s_waitcnt lgkmcnt(6)
	s_nop 0
	v_mfma_f32_32x32x16_bf16 v[34:49], v[66:69], v[214:217], v[34:49]
	ds_read_b64_tr_b16 v[214:215], v176 offset:0x600
	ds_read_b64_tr_b16 v[216:217], v176 offset:0xe00
	s_waitcnt lgkmcnt(6)
	s_nop 0
	v_mfma_f32_32x32x16_bf16 v[34:49], v[70:73], v[218:221], v[34:49]
	ds_read_b64_tr_b16 v[218:219], v176 offset:0x1600
	ds_read_b64_tr_b16 v[220:221], v176 offset:0x1e00
	s_waitcnt lgkmcnt(6)
	s_nop 0
	v_mfma_f32_32x32x16_bf16 v[34:49], v[74:77], v[222:225], v[34:49]
	ds_read_b64_tr_b16 v[222:223], v176 offset:0x2600
	ds_read_b64_tr_b16 v[224:225], v176 offset:0x2e00
	s_waitcnt lgkmcnt(6)
	s_nop 0
	v_mfma_f32_32x32x16_bf16 v[34:49], v[78:81], v[226:229], v[34:49]
	ds_read_b64_tr_b16 v[226:227], v176 offset:0x3600
	ds_read_b64_tr_b16 v[228:229], v176 offset:0x3e00
	s_waitcnt lgkmcnt(6)
	s_waitcnt lgkmcnt(4)
	s_waitcnt lgkmcnt(2)
	s_nop 0
	s_waitcnt lgkmcnt(0)
	v_mfma_f32_32x32x16_bf16 v[50:65], v[66:69], v[214:217], v[50:65]
	s_barrier
	s_waitcnt vmcnt(4)
	s_nop 0
	s_nop 0
	s_nop 0
	v_mfma_f32_32x32x16_bf16 v[50:65], v[70:73], v[218:221], v[50:65]
	s_nop 0
	s_nop 0
	s_nop 0
	s_nop 0
	s_nop 0
	v_mfma_f32_32x32x16_bf16 v[50:65], v[74:77], v[222:225], v[50:65]
	s_nop 0
	s_nop 0
	s_nop 0
	s_nop 0
	v_mfma_f32_32x32x16_bf16 v[50:65], v[78:81], v[226:229], v[50:65]
	s_nop 0
	s_nop 0
	s_nop 0
	s_nop 0
	v_exp_f32_e32 v202, v98
	v_exp_f32_e32 v203, v99
	v_exp_f32_e32 v206, v100
	v_exp_f32_e32 v207, v101
	v_exp_f32_e32 v222, v102
	v_exp_f32_e32 v223, v103
	v_exp_f32_e32 v224, v104
	v_exp_f32_e32 v225, v105
	v_exp_f32_e32 v226, v106
	v_exp_f32_e32 v227, v107
	v_exp_f32_e32 v228, v108
	v_exp_f32_e32 v229, v109
	v_exp_f32_e32 v232, v110
	v_exp_f32_e32 v233, v111
	v_exp_f32_e32 v234, v112
	v_exp_f32_e32 v235, v113
	s_waitcnt vmcnt(7)
	ds_write_b128 v177, v[130:133]
	s_waitcnt vmcnt(5)
	ds_write_b128 v185, v[134:137]
	ds_write_b128 v197, v[138:141] offset:32768
	s_waitcnt vmcnt(4)
	ds_write_b128 v198, v[142:145] offset:32768
	s_waitcnt lgkmcnt(0)
	s_barrier
	ds_read_b128 v[66:69], v212 offset:32768
	ds_read_b128 v[70:73], v212 offset:40960
	ds_read_b128 v[214:217], v213 offset:32768
	ds_read_b128 v[218:221], v213 offset:40960
	s_nop 0
	s_waitcnt lgkmcnt(3)
	v_mfma_f32_32x32x16_bf16 v[98:113], v[66:69], v[126:129], 0
	s_nop 0
	v_exp_f32_e32 v82, v82
	s_nop 0
	s_nop 0
	s_nop 0
	v_exp_f32_e32 v83, v83
	s_waitcnt lgkmcnt(2)
	v_mfma_f32_32x32x16_bf16 v[66:81], v[70:73], v[126:129], 0
	s_nop 0
	v_exp_f32_e32 v84, v84
	s_nop 0
	s_waitcnt lgkmcnt(1)
	v_mfma_f32_32x32x16_bf16 v[98:113], v[214:217], v[122:125], v[98:113]
	v_exp_f32_e32 v85, v85
	s_nop 0
	s_nop 0
	v_exp_f32_e32 v89, v89
	s_waitcnt lgkmcnt(0)
	v_mfma_f32_32x32x16_bf16 v[66:81], v[218:221], v[122:125], v[66:81]
	ds_read_b128 v[214:217], v199 offset:32768
	ds_read_b128 v[218:221], v199 offset:40960
	s_nop 0
	s_nop 0
	s_nop 0
	s_waitcnt lgkmcnt(1)
	v_mfma_f32_32x32x16_bf16 v[98:113], v[214:217], v[118:121], v[98:113]
	v_exp_f32_e32 v236, v93
	s_nop 0
	s_nop 0
	v_exp_f32_e32 v237, v94
	s_nop 0
	s_waitcnt lgkmcnt(0)
	v_mfma_f32_32x32x16_bf16 v[66:81], v[218:221], v[118:121], v[66:81]
	ds_read_b128 v[214:217], v196 offset:32768
	ds_read_b128 v[218:221], v196 offset:40960
	v_exp_f32_e32 v238, v95
	s_nop 0
	v_exp_f32_e32 v239, v96
	v_cvt_pk_bf16_f32 v94, v202, v203
	s_waitcnt lgkmcnt(1)
	v_mfma_f32_32x32x16_bf16 v[98:113], v[214:217], v[114:117], v[98:113]
	v_exp_f32_e32 v216, v86
	v_exp_f32_e32 v217, v87
	v_add_f32_e32 v86, 0, v202
	v_add_f32_e32 v87, 0, v82
	v_exp_f32_e32 v240, v97
	v_add_f32_e32 v86, v203, v86
	v_add_f32_e32 v87, v83, v87
	s_waitcnt lgkmcnt(0)
	v_mfma_f32_32x32x16_bf16 v[66:81], v[218:221], v[114:117], v[66:81]
	v_add_f32_e32 v86, v206, v86
	v_add_f32_e32 v87, v84, v87
	v_exp_f32_e32 v218, v88
	v_add_f32_e32 v86, v207, v86
	v_add_f32_e32 v87, v85, v87
	v_exp_f32_e32 v219, v90
	v_add_f32_e32 v86, v222, v86
	v_add_f32_e32 v87, v216, v87
	v_exp_f32_e32 v220, v91
	v_add_f32_e32 v86, v223, v86
	v_add_f32_e32 v87, v217, v87
	v_exp_f32_e32 v221, v92
	v_add_f32_e32 v86, v224, v86
	v_add_f32_e32 v87, v218, v87
	v_cvt_pk_bf16_f32 v95, v206, v207
	v_add_f32_e32 v86, v225, v86
	v_add_f32_e32 v87, v89, v87
	v_cvt_pk_bf16_f32 v96, v222, v223
	v_add_f32_e32 v86, v226, v86
	v_add_f32_e32 v87, v219, v87
	v_cvt_pk_bf16_f32 v97, v224, v225
	v_add_f32_e32 v86, v227, v86
	v_add_f32_e32 v87, v220, v87
	v_cvt_pk_bf16_f32 v90, v226, v227
	v_add_f32_e32 v86, v228, v86
	v_add_f32_e32 v87, v221, v87
	v_cvt_pk_bf16_f32 v91, v228, v229
	v_add_f32_e32 v86, v229, v86
	v_add_f32_e32 v87, v236, v87
	v_cvt_pk_bf16_f32 v92, v232, v233
	v_add_f32_e32 v86, v232, v86
	v_add_f32_e32 v87, v237, v87
	v_cvt_pk_bf16_f32 v93, v234, v235
	v_add_f32_e32 v86, v233, v86
	v_add_f32_e32 v87, v238, v87
	v_cvt_pk_bf16_f32 v88, v216, v217
	v_add_f32_e32 v86, v234, v86
	v_add_f32_e32 v87, v239, v87
	v_cvt_pk_bf16_f32 v89, v218, v89
	v_add_f32_e32 v86, v235, v86
	v_add_f32_e32 v87, v240, v87
	v_permlane32_swap_b32_e32 v94, v96
	v_add_f32_e32 v214, v86, v87
	v_mov_b32_e32 v215, v214
	v_cvt_pk_bf16_f32 v86, v82, v83
	v_cvt_pk_bf16_f32 v87, v84, v85
	v_cvt_pk_bf16_f32 v82, v219, v220
	v_cvt_pk_bf16_f32 v83, v221, v236
	v_cvt_pk_bf16_f32 v84, v237, v238
	v_cvt_pk_bf16_f32 v85, v239, v240
	v_permlane32_swap_b32_e32 v214, v215
	v_permlane32_swap_b32_e32 v95, v97
	v_permlane32_swap_b32_e32 v90, v92
	v_permlane32_swap_b32_e32 v91, v93
	v_permlane32_swap_b32_e32 v86, v88
	v_permlane32_swap_b32_e32 v87, v89
	v_permlane32_swap_b32_e32 v82, v84
	v_permlane32_swap_b32_e32 v83, v85
	s_cmp_gt_u32 s4, 28
	s_cselect_b64 s[0:1], -1, 0
	s_and_b64 vcc, exec, s[0:1]
	s_cbranch_vccnz .LBB0_282
	v_add_co_u32_e32 v134, vcc, 0xfffd0000, v166
	s_nop 1
	v_addc_co_u32_e32 v135, vcc, -1, v167, vcc
	global_load_dwordx4 v[130:133], v[134:135], off
	global_load_dwordx4 v[138:141], v[134:135], off offset:-2048
	s_nop 0
	global_load_dwordx4 v[134:137], v[166:167], off
	global_load_dwordx4 v[142:145], v[166:167], off offset:-2048
	s_branch .LBB0_282
.LBB0_285:
	s_and_b32 s0, s24, 0x3fffffc0
	s_lshl_b32 s0, s0, 2
	s_add_i32 s4, s0, 0
	s_add_i32 s4, s4, 0x10000
	ds_read_b128 v[82:85], v212 offset:49152
	ds_read_b128 v[86:89], v212 offset:57344
	s_nop 0
	s_nop 0
	s_waitcnt lgkmcnt(1)
	v_mfma_f32_32x32x16_bf16 v[98:113], v[82:85], v[126:129], 0
	s_nop 0
	s_nop 0
	s_nop 0
	s_waitcnt lgkmcnt(0)
	v_mfma_f32_32x32x16_bf16 v[82:97], v[86:89], v[126:129], 0
	ds_read_b128 v[126:129], v213 offset:49152
	ds_read_b128 v[130:133], v213 offset:57344
	s_nop 0
	s_nop 0
	s_nop 0
	s_waitcnt lgkmcnt(1)
	v_mfma_f32_32x32x16_bf16 v[98:113], v[126:129], v[122:125], v[98:113]
	s_nop 0
	s_nop 0
	s_nop 0
	s_nop 0
	s_waitcnt lgkmcnt(0)
	v_mfma_f32_32x32x16_bf16 v[82:97], v[130:133], v[122:125], v[82:97]
	ds_read_b128 v[122:125], v199 offset:49152
	ds_read_b128 v[126:129], v199 offset:57344
	s_nop 0
	s_nop 0
	s_nop 0
	s_waitcnt lgkmcnt(1)
	v_mfma_f32_32x32x16_bf16 v[98:113], v[122:125], v[118:121], v[98:113]
	s_nop 0
	v_exp_f32_e32 v130, v80
	s_nop 0
	v_exp_f32_e32 v81, v81
	s_waitcnt lgkmcnt(0)
	v_mfma_f32_32x32x16_bf16 v[82:97], v[126:129], v[118:121], v[82:97]
	ds_read_b128 v[118:121], v196 offset:49152
	ds_read_b128 v[122:125], v196 offset:57344
	v_exp_f32_e32 v126, v76
	v_exp_f32_e32 v127, v77
	v_exp_f32_e32 v128, v78
	v_exp_f32_e32 v129, v79
	v_cvt_pk_bf16_f32 v79, v126, v127
	s_waitcnt lgkmcnt(1)
	v_mfma_f32_32x32x16_bf16 v[98:113], v[118:121], v[114:117], v[98:113]
	v_exp_f32_e32 v118, v68
	v_exp_f32_e32 v119, v69
	v_exp_f32_e32 v120, v70
	v_exp_f32_e32 v121, v71
	v_cvt_pk_bf16_f32 v68, v226, v227
	v_cvt_pk_bf16_f32 v69, v228, v229
	v_cvt_pk_bf16_f32 v70, v214, v215
	s_waitcnt lgkmcnt(0)
	v_mfma_f32_32x32x16_bf16 v[82:97], v[122:125], v[114:117], v[82:97]
	v_exp_f32_e32 v115, v66
	v_exp_f32_e32 v117, v67
	v_add_f32_e32 v66, 0, v217
	v_add_f32_e32 v67, 0, v115
	v_add_f32_e32 v66, v222, v66
	v_add_f32_e32 v67, v117, v67
	v_exp_f32_e32 v122, v72
	v_add_f32_e32 v66, v223, v66
	v_add_f32_e32 v67, v118, v67
	v_exp_f32_e32 v123, v73
	v_add_f32_e32 v66, v225, v66
	v_add_f32_e32 v67, v119, v67
	v_exp_f32_e32 v124, v74
	v_add_f32_e32 v66, v226, v66
	v_add_f32_e32 v67, v120, v67
	v_exp_f32_e32 v125, v75
	v_add_f32_e32 v66, v227, v66
	v_add_f32_e32 v67, v121, v67
	v_cvt_pk_bf16_f32 v71, v216, v218
	v_add_f32_e32 v66, v228, v66
	v_add_f32_e32 v67, v122, v67
	v_cvt_pk_bf16_f32 v72, v219, v220
	v_add_f32_e32 v66, v229, v66
	v_add_f32_e32 v67, v123, v67
	v_cvt_pk_bf16_f32 v73, v221, v224
	v_add_f32_e32 v66, v214, v66
	v_add_f32_e32 v67, v124, v67
	v_cvt_pk_bf16_f32 v74, v115, v117
	v_add_f32_e32 v66, v215, v66
	v_add_f32_e32 v67, v125, v67
	v_cvt_pk_bf16_f32 v75, v118, v119
	v_add_f32_e32 v66, v216, v66
	v_add_f32_e32 v67, v126, v67
	v_cvt_pk_bf16_f32 v76, v120, v121
	v_add_f32_e32 v66, v218, v66
	v_add_f32_e32 v67, v127, v67
	v_cvt_pk_bf16_f32 v77, v122, v123
	v_add_f32_e32 v66, v219, v66
	v_add_f32_e32 v67, v128, v67
	v_cvt_pk_bf16_f32 v78, v124, v125
	v_add_f32_e32 v66, v220, v66
	v_add_f32_e32 v67, v129, v67
	v_cvt_pk_bf16_f32 v80, v128, v129
	v_add_f32_e32 v66, v221, v66
	v_add_f32_e32 v67, v130, v67
	v_permlane32_swap_b32_e32 v70, v72
	v_add_f32_e32 v66, v224, v66
	v_add_f32_e32 v67, v81, v67
	v_cvt_pk_bf16_f32 v81, v130, v81
	v_add_f32_e32 v114, v66, v67
	v_mov_b32_e32 v116, v114
	s_nop 1
	v_permlane32_swap_b32_e32 v114, v116
	v_cvt_pk_bf16_f32 v66, v217, v222
	v_cvt_pk_bf16_f32 v67, v223, v225
	s_nop 0
	v_permlane32_swap_b32_e32 v66, v68
	v_permlane32_swap_b32_e32 v67, v69
	v_permlane32_swap_b32_e32 v71, v73
	v_permlane32_swap_b32_e32 v74, v76
	v_permlane32_swap_b32_e32 v75, v77
	v_permlane32_swap_b32_e32 v78, v80
	v_permlane32_swap_b32_e32 v79, v81
	ds_read_b64_tr_b16 v[118:119], v176 offset:0
	ds_read_b64_tr_b16 v[120:121], v176 offset:0x800
	ds_read_b64_tr_b16 v[122:123], v176 offset:0x1000
	ds_read_b64_tr_b16 v[124:125], v176 offset:0x1800
	ds_read_b64_tr_b16 v[126:127], v176 offset:0x2000
	ds_read_b64_tr_b16 v[128:129], v176 offset:0x2800
	ds_read_b64_tr_b16 v[130:131], v176 offset:0x3000
	ds_read_b64_tr_b16 v[132:133], v176 offset:0x3800
	s_nop 0
	s_waitcnt lgkmcnt(6)
	s_nop 0
	v_mfma_f32_32x32x16_bf16 v[2:17], v[66:69], v[118:121], v[2:17]
	ds_read_b64_tr_b16 v[118:119], v176 offset:0x200
	ds_read_b64_tr_b16 v[120:121], v176 offset:0xa00
	s_waitcnt lgkmcnt(6)
	s_nop 0
	v_exp_f32_e32 v82, v82
	v_mfma_f32_32x32x16_bf16 v[2:17], v[70:73], v[122:125], v[2:17]
	ds_read_b64_tr_b16 v[122:123], v176 offset:0x1200
	ds_read_b64_tr_b16 v[124:125], v176 offset:0x1a00
	s_waitcnt lgkmcnt(6)
	s_nop 0
	v_exp_f32_e32 v83, v83
	s_nop 0
	v_mfma_f32_32x32x16_bf16 v[2:17], v[74:77], v[126:129], v[2:17]
	ds_read_b64_tr_b16 v[126:127], v176 offset:0x2200
	ds_read_b64_tr_b16 v[128:129], v176 offset:0x2a00
	s_waitcnt lgkmcnt(6)
	v_exp_f32_e32 v84, v84
	s_nop 0
	v_exp_f32_e32 v85, v85
	v_mfma_f32_32x32x16_bf16 v[2:17], v[78:81], v[130:133], v[2:17]
	ds_read_b64_tr_b16 v[130:131], v176 offset:0x3200
	ds_read_b64_tr_b16 v[132:133], v176 offset:0x3a00
	s_waitcnt lgkmcnt(6)
	s_nop 0
	v_exp_f32_e32 v86, v86
	v_mfma_f32_32x32x16_bf16 v[18:33], v[66:69], v[118:121], v[18:33]
	ds_read_b64_tr_b16 v[118:119], v176 offset:0x400
	ds_read_b64_tr_b16 v[120:121], v176 offset:0xc00
	s_waitcnt lgkmcnt(6)
	s_nop 0
	v_exp_f32_e32 v87, v87
	s_nop 0
	v_mfma_f32_32x32x16_bf16 v[18:33], v[70:73], v[122:125], v[18:33]
	ds_read_b64_tr_b16 v[122:123], v176 offset:0x1400
	ds_read_b64_tr_b16 v[124:125], v176 offset:0x1c00
	s_waitcnt lgkmcnt(6)
	v_exp_f32_e32 v88, v88
	s_nop 0
	v_exp_f32_e32 v89, v89
	v_mfma_f32_32x32x16_bf16 v[18:33], v[74:77], v[126:129], v[18:33]
	ds_read_b64_tr_b16 v[126:127], v176 offset:0x2400
	ds_read_b64_tr_b16 v[128:129], v176 offset:0x2c00
	s_waitcnt lgkmcnt(6)
	s_nop 0
	v_exp_f32_e32 v90, v90
	v_mfma_f32_32x32x16_bf16 v[18:33], v[78:81], v[130:133], v[18:33]
	ds_read_b64_tr_b16 v[130:131], v176 offset:0x3400
	ds_read_b64_tr_b16 v[132:133], v176 offset:0x3c00
	s_waitcnt lgkmcnt(6)
	s_nop 0
	v_exp_f32_e32 v91, v91
	s_nop 0
	v_mfma_f32_32x32x16_bf16 v[34:49], v[66:69], v[118:121], v[34:49]
	ds_read_b64_tr_b16 v[118:119], v176 offset:0x600
	ds_read_b64_tr_b16 v[120:121], v176 offset:0xe00
	s_waitcnt lgkmcnt(6)
	v_exp_f32_e32 v92, v92
	s_nop 0
	v_exp_f32_e32 v93, v93
	v_mfma_f32_32x32x16_bf16 v[34:49], v[70:73], v[122:125], v[34:49]
	ds_read_b64_tr_b16 v[122:123], v176 offset:0x1600
	ds_read_b64_tr_b16 v[124:125], v176 offset:0x1e00
	s_waitcnt lgkmcnt(6)
	s_nop 0
	v_exp_f32_e32 v94, v94
	v_mfma_f32_32x32x16_bf16 v[34:49], v[74:77], v[126:129], v[34:49]
	ds_read_b64_tr_b16 v[126:127], v176 offset:0x2600
	ds_read_b64_tr_b16 v[128:129], v176 offset:0x2e00
	s_waitcnt lgkmcnt(6)
	s_nop 0
	v_exp_f32_e32 v95, v95
	s_nop 0
	v_mfma_f32_32x32x16_bf16 v[34:49], v[78:81], v[130:133], v[34:49]
	ds_read_b64_tr_b16 v[130:131], v176 offset:0x3600
	ds_read_b64_tr_b16 v[132:133], v176 offset:0x3e00
	s_waitcnt lgkmcnt(6)
	s_waitcnt lgkmcnt(4)
	s_waitcnt lgkmcnt(2)
	v_exp_f32_e32 v96, v96
	s_waitcnt lgkmcnt(0)
	v_mfma_f32_32x32x16_bf16 v[50:65], v[66:69], v[118:121], v[50:65]
	s_nop 0
	s_nop 0
	v_exp_f32_e32 v66, v98
	s_nop 0
	v_exp_f32_e32 v67, v99
	s_nop 0
	v_exp_f32_e32 v68, v100
	v_add_f32_e32 v98, 0, v66
	v_add_f32_e32 v99, 0, v82
	v_mfma_f32_32x32x16_bf16 v[50:65], v[70:73], v[122:125], v[50:65]
	s_nop 0
	v_exp_f32_e32 v69, v101
	v_add_f32_e32 v98, v67, v98
	v_add_f32_e32 v99, v83, v99
	s_nop 0
	v_exp_f32_e32 v70, v102
	v_add_f32_e32 v98, v68, v98
	v_add_f32_e32 v99, v84, v99
	s_nop 0
	v_exp_f32_e32 v71, v103
	v_add_f32_e32 v98, v69, v98
	v_add_f32_e32 v99, v85, v99
	s_nop 0
	v_exp_f32_e32 v72, v104
	v_add_f32_e32 v98, v70, v98
	v_add_f32_e32 v99, v86, v99
	v_mfma_f32_32x32x16_bf16 v[50:65], v[74:77], v[126:129], v[50:65]
	s_nop 0
	v_exp_f32_e32 v73, v105
	v_add_f32_e32 v98, v71, v98
	v_add_f32_e32 v99, v87, v99
	s_nop 0
	v_exp_f32_e32 v74, v106
	v_add_f32_e32 v98, v72, v98
	v_add_f32_e32 v99, v88, v99
	s_nop 0
	v_exp_f32_e32 v75, v107
	v_add_f32_e32 v98, v73, v98
	v_add_f32_e32 v99, v89, v99
	s_nop 0
	v_exp_f32_e32 v76, v108
	v_add_f32_e32 v98, v74, v98
	v_add_f32_e32 v99, v90, v99
	v_mfma_f32_32x32x16_bf16 v[50:65], v[78:81], v[130:133], v[50:65]
	s_nop 0
	v_exp_f32_e32 v77, v109
	v_add_f32_e32 v98, v75, v98
	v_add_f32_e32 v99, v91, v99
	s_nop 0
	v_exp_f32_e32 v78, v110
	v_add_f32_e32 v98, v76, v98
	v_add_f32_e32 v99, v92, v99
	s_nop 0
	v_exp_f32_e32 v79, v111
	v_add_f32_e32 v98, v77, v98
	v_add_f32_e32 v99, v93, v99
	s_nop 0
	v_exp_f32_e32 v80, v112
	v_add_f32_e32 v98, v78, v98
	v_add_f32_e32 v99, v94, v99
	v_cvt_pk_bf16_f32 v66, v66, v67
	v_exp_f32_e32 v81, v113
	v_exp_f32_e32 v97, v97
	v_add_f32_e32 v98, v79, v98
	v_add_f32_e32 v99, v95, v99
	v_cvt_pk_bf16_f32 v67, v68, v69
	v_add_f32_e32 v98, v80, v98
	v_add_f32_e32 v99, v96, v99
	v_cvt_pk_bf16_f32 v68, v70, v71
	v_add_f32_e32 v98, v81, v98
	v_add_f32_e32 v99, v97, v99
	v_cvt_pk_bf16_f32 v69, v72, v73
	v_add_f32_e32 v115, v98, v99
	v_mov_b32_e32 v117, v115
	s_nop 1
	v_permlane32_swap_b32_e32 v115, v117
	v_cvt_pk_bf16_f32 v70, v74, v75
	v_cvt_pk_bf16_f32 v71, v76, v77
	v_cvt_pk_bf16_f32 v72, v78, v79
	v_cvt_pk_bf16_f32 v73, v80, v81
	v_cvt_pk_bf16_f32 v74, v82, v83
	v_cvt_pk_bf16_f32 v75, v84, v85
	v_cvt_pk_bf16_f32 v76, v86, v87
	v_cvt_pk_bf16_f32 v77, v88, v89
	v_cvt_pk_bf16_f32 v78, v90, v91
	v_cvt_pk_bf16_f32 v79, v92, v93
	v_cvt_pk_bf16_f32 v80, v94, v95
	v_cvt_pk_bf16_f32 v81, v96, v97
	s_barrier
	v_permlane32_swap_b32_e32 v66, v68
	v_permlane32_swap_b32_e32 v67, v69
	v_permlane32_swap_b32_e32 v70, v72
	v_permlane32_swap_b32_e32 v71, v73
	v_permlane32_swap_b32_e32 v74, v76
	v_permlane32_swap_b32_e32 v75, v77
	v_permlane32_swap_b32_e32 v78, v80
	v_permlane32_swap_b32_e32 v79, v81
	ds_read_b64_tr_b16 v[82:83], v175 offset:0
	ds_read_b64_tr_b16 v[84:85], v175 offset:0x800
	ds_read_b64_tr_b16 v[86:87], v175 offset:0x1000
	ds_read_b64_tr_b16 v[88:89], v175 offset:0x1800
	ds_read_b64_tr_b16 v[90:91], v175 offset:0x2000
	ds_read_b64_tr_b16 v[92:93], v175 offset:0x2800
	ds_read_b64_tr_b16 v[94:95], v175 offset:0x3000
	ds_read_b64_tr_b16 v[96:97], v175 offset:0x3800
	s_nop 0
	s_waitcnt lgkmcnt(6)
	v_cmp_gt_u32_e32 vcc, 32, v172
	v_mfma_f32_32x32x16_bf16 v[2:17], v[66:69], v[82:85], v[2:17]
	ds_read_b64_tr_b16 v[82:83], v175 offset:0x200
	ds_read_b64_tr_b16 v[84:85], v175 offset:0xa00
	s_waitcnt lgkmcnt(6)
	s_nop 0
	v_mfma_f32_32x32x16_bf16 v[2:17], v[70:73], v[86:89], v[2:17]
	ds_read_b64_tr_b16 v[86:87], v175 offset:0x1200
	ds_read_b64_tr_b16 v[88:89], v175 offset:0x1a00
	s_waitcnt lgkmcnt(6)
	s_nop 0
	v_mfma_f32_32x32x16_bf16 v[2:17], v[74:77], v[90:93], v[2:17]
	ds_read_b64_tr_b16 v[90:91], v175 offset:0x2200
	ds_read_b64_tr_b16 v[92:93], v175 offset:0x2a00
	s_waitcnt lgkmcnt(6)
	s_nop 0
	v_mfma_f32_32x32x16_bf16 v[2:17], v[78:81], v[94:97], v[2:17]
	ds_read_b64_tr_b16 v[94:95], v175 offset:0x3200
	ds_read_b64_tr_b16 v[96:97], v175 offset:0x3a00
	s_waitcnt lgkmcnt(6)
	s_nop 0
	v_mfma_f32_32x32x16_bf16 v[18:33], v[66:69], v[82:85], v[18:33]
	ds_read_b64_tr_b16 v[82:83], v175 offset:0x400
	ds_read_b64_tr_b16 v[84:85], v175 offset:0xc00
	s_waitcnt lgkmcnt(6)
	s_nop 0
	v_mfma_f32_32x32x16_bf16 v[18:33], v[70:73], v[86:89], v[18:33]
	ds_read_b64_tr_b16 v[86:87], v175 offset:0x1400
	ds_read_b64_tr_b16 v[88:89], v175 offset:0x1c00
	s_waitcnt lgkmcnt(6)
	s_nop 0
	v_mfma_f32_32x32x16_bf16 v[18:33], v[74:77], v[90:93], v[18:33]
	ds_read_b64_tr_b16 v[90:91], v175 offset:0x2400
	ds_read_b64_tr_b16 v[92:93], v175 offset:0x2c00
	s_waitcnt lgkmcnt(6)
	s_nop 0
	v_mfma_f32_32x32x16_bf16 v[18:33], v[78:81], v[94:97], v[18:33]
	ds_read_b64_tr_b16 v[94:95], v175 offset:0x3400
	ds_read_b64_tr_b16 v[96:97], v175 offset:0x3c00
	s_waitcnt lgkmcnt(6)
	s_nop 0
	v_mfma_f32_32x32x16_bf16 v[34:49], v[66:69], v[82:85], v[34:49]
	ds_read_b64_tr_b16 v[82:83], v175 offset:0x600
	ds_read_b64_tr_b16 v[84:85], v175 offset:0xe00
	s_waitcnt lgkmcnt(6)
	s_nop 0
	v_mfma_f32_32x32x16_bf16 v[34:49], v[70:73], v[86:89], v[34:49]
	ds_read_b64_tr_b16 v[86:87], v175 offset:0x1600
	ds_read_b64_tr_b16 v[88:89], v175 offset:0x1e00
	s_waitcnt lgkmcnt(6)
	s_nop 0
	v_mfma_f32_32x32x16_bf16 v[34:49], v[74:77], v[90:93], v[34:49]
	ds_read_b64_tr_b16 v[90:91], v175 offset:0x2600
	ds_read_b64_tr_b16 v[92:93], v175 offset:0x2e00
	s_waitcnt lgkmcnt(6)
	s_nop 0
	v_mfma_f32_32x32x16_bf16 v[34:49], v[78:81], v[94:97], v[34:49]
	ds_read_b64_tr_b16 v[94:95], v175 offset:0x3600
	ds_read_b64_tr_b16 v[96:97], v175 offset:0x3e00
	s_waitcnt lgkmcnt(6)
	s_waitcnt lgkmcnt(4)
	s_waitcnt lgkmcnt(2)
	s_nop 0
	s_waitcnt lgkmcnt(0)
	v_mfma_f32_32x32x16_bf16 v[50:65], v[66:69], v[82:85], v[50:65]
	v_mfma_f32_32x32x16_bf16 v[50:65], v[70:73], v[86:89], v[50:65]
	v_mfma_f32_32x32x16_bf16 v[50:65], v[74:77], v[90:93], v[50:65]
	v_mfma_f32_32x32x16_bf16 v[50:65], v[78:81], v[94:97], v[50:65]
	s_and_saveexec_b64 s[0:1], vcc
	v_pk_add_f32 v[66:67], v[114:115], v[116:117]
	v_lshl_add_u32 v68, v164, 2, s4
	v_add_f32_e32 v66, v174, v66
	v_add_f32_e32 v66, v66, v67
	ds_write_b32 v68, v66
	s_or_b64 exec, exec, s[0:1]
	s_waitcnt lgkmcnt(0)
	v_add_u32_e32 v100, s4, v178
	ds_read_b128 v[66:69], v100
	ds_read_b128 v[70:73], v100 offset:32
	v_mov_b32_e32 v74, v2
	v_mov_b32_e32 v75, v18
	v_mov_b32_e32 v18, v3
	s_waitcnt lgkmcnt(1)
	v_rcp_f32_e32 v66, v66
	v_rcp_f32_e32 v2, v67
	s_lshl_b32 s0, s28, 14
	s_add_i32 s0, s0, 0
	v_pk_mul_f32 v[92:93], v[74:75], v[66:67] op_sel_hi:[1,0]
	v_mov_b32_e32 v75, v50
	v_mov_b32_e32 v50, v35
	v_pk_mul_f32 v[96:97], v[18:19], v[2:3] op_sel_hi:[1,0]
	v_pk_mul_f32 v[98:99], v[50:51], v[2:3] op_sel_hi:[1,0]
	v_rcp_f32_e32 v2, v68
	v_mov_b32_e32 v18, v4
	v_mov_b32_e32 v19, v20
	v_mov_b32_e32 v20, v5
	v_pk_mul_f32 v[90:91], v[18:19], v[2:3] op_sel_hi:[1,0]
	v_mov_b32_e32 v18, v36
	v_mov_b32_e32 v19, v52
	v_pk_mul_f32 v[18:19], v[18:19], v[2:3] op_sel_hi:[1,0]
	v_rcp_f32_e32 v2, v69
	v_mov_b32_e32 v52, v37
	v_mov_b32_e32 v4, v6
	v_mov_b32_e32 v5, v22
	v_pk_mul_f32 v[88:89], v[20:21], v[2:3] op_sel_hi:[1,0]
	v_pk_mul_f32 v[86:87], v[52:53], v[2:3] op_sel_hi:[1,0]
	s_waitcnt lgkmcnt(0)
	v_rcp_f32_e32 v2, v70
	v_mov_b32_e32 v74, v34
	v_mov_b32_e32 v22, v7
	v_pk_mul_f32 v[94:95], v[74:75], v[66:67] op_sel_hi:[1,0]
	v_pk_mul_f32 v[84:85], v[4:5], v[2:3] op_sel_hi:[1,0]
	v_mov_b32_e32 v4, v38
	v_mov_b32_e32 v5, v54
	v_pk_mul_f32 v[34:35], v[4:5], v[2:3] op_sel_hi:[1,0]
	v_rcp_f32_e32 v2, v71
	v_mov_b32_e32 v54, v39
	v_mov_b32_e32 v4, v8
	v_mov_b32_e32 v5, v24
	v_pk_mul_f32 v[82:83], v[22:23], v[2:3] op_sel_hi:[1,0]
	v_pk_mul_f32 v[80:81], v[54:55], v[2:3] op_sel_hi:[1,0]
	v_rcp_f32_e32 v2, v72
	v_mov_b32_e32 v24, v9
	v_mov_b32_e32 v6, v10
	v_mov_b32_e32 v7, v26
	v_pk_mul_f32 v[78:79], v[4:5], v[2:3] op_sel_hi:[1,0]
	v_mov_b32_e32 v4, v40
	v_mov_b32_e32 v5, v56
	v_pk_mul_f32 v[76:77], v[4:5], v[2:3] op_sel_hi:[1,0]
	v_rcp_f32_e32 v2, v73
	v_mov_b32_e32 v56, v41
	v_mov_b32_e32 v26, v11
	v_lshlrev_b32_e32 v8, 2, v164
	v_pk_mul_f32 v[74:75], v[24:25], v[2:3] op_sel_hi:[1,0]
	v_pk_mul_f32 v[72:73], v[56:57], v[2:3] op_sel_hi:[1,0]
	ds_read_b128 v[2:5], v100 offset:64
	s_cmp_lg_u32 s25, 1
	v_lshl_add_u32 v104, v172, 2, s0
	s_waitcnt lgkmcnt(0)
	v_rcp_f32_e32 v2, v2
	s_nop 0
	v_pk_mul_f32 v[70:71], v[6:7], v[2:3] op_sel_hi:[1,0]
	v_mov_b32_e32 v6, v42
	v_mov_b32_e32 v7, v58
	v_pk_mul_f32 v[66:67], v[6:7], v[2:3] op_sel_hi:[1,0]
	v_rcp_f32_e32 v2, v3
	v_mov_b32_e32 v58, v43
	v_mov_b32_e32 v6, v12
	v_mov_b32_e32 v7, v28
	v_pk_mul_f32 v[68:69], v[26:27], v[2:3] op_sel_hi:[1,0]
	v_pk_mul_f32 v[56:57], v[58:59], v[2:3] op_sel_hi:[1,0]
	v_rcp_f32_e32 v2, v4
	v_mov_b32_e32 v28, v13
	v_pk_mul_f32 v[54:55], v[6:7], v[2:3] op_sel_hi:[1,0]
	v_mov_b32_e32 v6, v44
	v_mov_b32_e32 v7, v60
	v_pk_mul_f32 v[50:51], v[6:7], v[2:3] op_sel_hi:[1,0]
	v_rcp_f32_e32 v2, v5
	v_mov_b32_e32 v60, v45
	v_mov_b32_e32 v6, v14
	v_mov_b32_e32 v7, v30
	v_pk_mul_f32 v[52:53], v[28:29], v[2:3] op_sel_hi:[1,0]
	v_pk_mul_f32 v[44:45], v[60:61], v[2:3] op_sel_hi:[1,0]
	ds_read_b128 v[2:5], v100 offset:96
	s_waitcnt lgkmcnt(0)
	s_barrier
	global_load_dword v103, v8, s[12:13]
	global_load_dword v102, v8, s[12:13] offset:128
	global_load_dword v101, v8, s[12:13] offset:256
	global_load_dword v100, v8, s[12:13] offset:384
	v_rcp_f32_e32 v2, v2
	v_mov_b32_e32 v30, v15
	v_pk_mul_f32 v[42:43], v[6:7], v[2:3] op_sel_hi:[1,0]
	v_mov_b32_e32 v6, v46
	v_mov_b32_e32 v7, v62
	v_pk_mul_f32 v[38:39], v[6:7], v[2:3] op_sel_hi:[1,0]
	v_rcp_f32_e32 v2, v3
	v_mov_b32_e32 v62, v47
	v_mov_b32_e32 v6, v16
	v_mov_b32_e32 v7, v32
	v_pk_mul_f32 v[40:41], v[30:31], v[2:3] op_sel_hi:[1,0]
	v_pk_mul_f32 v[36:37], v[62:63], v[2:3] op_sel_hi:[1,0]
	v_rcp_f32_e32 v2, v4
	v_mov_b32_e32 v32, v17
	v_pk_mul_f32 v[26:27], v[6:7], v[2:3] op_sel_hi:[1,0]
	v_mov_b32_e32 v6, v48
	v_mov_b32_e32 v7, v64
	v_pk_mul_f32 v[6:7], v[6:7], v[2:3] op_sel_hi:[1,0]
	v_rcp_f32_e32 v2, v5
	v_mov_b32_e32 v64, v49
	v_pk_mul_f32 v[4:5], v[32:33], v[2:3] op_sel_hi:[1,0]
	v_pk_mul_f32 v[2:3], v[64:65], v[2:3] op_sel_hi:[1,0]
	s_cbranch_scc1 .LBB0_289
	ds_write2st64_b32 v104, v92, v96 offset1:1
	ds_write2st64_b32 v104, v90, v88 offset0:2 offset1:3
	ds_write2st64_b32 v104, v84, v82 offset0:4 offset1:5
	ds_write2st64_b32 v104, v78, v74 offset0:6 offset1:7
	ds_write2st64_b32 v104, v70, v68 offset0:8 offset1:9
	ds_write2st64_b32 v104, v54, v52 offset0:10 offset1:11
	ds_write2st64_b32 v104, v42, v40 offset0:12 offset1:13
	ds_write2st64_b32 v104, v26, v4 offset0:14 offset1:15
	ds_write2st64_b32 v104, v93, v97 offset0:16 offset1:17
	ds_write2st64_b32 v104, v91, v89 offset0:18 offset1:19
	ds_write2st64_b32 v104, v85, v83 offset0:20 offset1:21
	ds_write2st64_b32 v104, v79, v75 offset0:22 offset1:23
	ds_write2st64_b32 v104, v71, v69 offset0:24 offset1:25
	ds_write2st64_b32 v104, v55, v53 offset0:26 offset1:27
	ds_write2st64_b32 v104, v43, v41 offset0:28 offset1:29
	ds_write2st64_b32 v104, v27, v5 offset0:30 offset1:31
	ds_write2st64_b32 v104, v94, v98 offset0:32 offset1:33
	ds_write2st64_b32 v104, v18, v86 offset0:34 offset1:35
	ds_write2st64_b32 v104, v34, v80 offset0:36 offset1:37
	ds_write2st64_b32 v104, v76, v72 offset0:38 offset1:39
	ds_write2st64_b32 v104, v66, v56 offset0:40 offset1:41
	ds_write2st64_b32 v104, v50, v44 offset0:42 offset1:43
	ds_write2st64_b32 v104, v38, v36 offset0:44 offset1:45
	ds_write2st64_b32 v104, v6, v2 offset0:46 offset1:47
	ds_write2st64_b32 v104, v95, v99 offset0:48 offset1:49
	ds_write2st64_b32 v104, v19, v87 offset0:50 offset1:51
	ds_write2st64_b32 v104, v35, v81 offset0:52 offset1:53
	ds_write2st64_b32 v104, v77, v73 offset0:54 offset1:55
	ds_write2st64_b32 v104, v67, v57 offset0:56 offset1:57
	ds_write2st64_b32 v104, v51, v45 offset0:58 offset1:59
	ds_write2st64_b32 v104, v39, v37 offset0:60 offset1:61
	ds_write2st64_b32 v104, v7, v3 offset0:62 offset1:63
